# previous + hand-written phase 0: modulation GEMV with batched loads (64 rows in flight, readlane broadcast) and layer-0 weight conversion with the new transposer
# speedup vs baseline: 1.0666x; 1.0212x over previous
; DI void wconv_item(const Params& p, int l, int t, char* smem) {
;   u16* wt = (u16*)(p.ws + OFF_WT);
;   if (t < WC_T_IN) { wconv_tile<1>(p.w_in + (size_t)l * 1024 * WIN, 1024, WIN, wt + WT_IN, t % 16, t / 16, smem); return; }
;   t -= WC_T_IN;
;   if (t < WC_T_A) { wconv_tile<0>(p.w_branch_a + (size_t)l * 1024 * 1024, 1024, 1024, wt + WT_A, t % 16, t / 16, smem); return; }
;   t -= WC_T_A;
;   if (t < WC_T_B) { wconv_tile<0>(p.w_branch_b + (size_t)l * 512 * 1024, 512, 1024, wt + WT_B, t % 8, t / 8, smem); return; }
;   t -= WC_T_B;
;   if (t < WC_T_OUT) { wconv_tile<0>(p.w_out + (size_t)l * 1024 * 1024, 1024, 1024, wt + WT_OUT, t % 16, t / 16, smem); return; }
;   t -= WC_T_OUT;
;   if (t < WC_T_13) { wconv_tile<2>(p.ffn_w13 + (size_t)l * 1024 * 5632, 1024, 5632, wt + WT_13, t % 16, t / 16, smem); return; }
;   t -= WC_T_13;
;   if (t < WC_T_2) { wconv_tile<0>(p.ffn_w2 + (size_t)l * FFN * 1024, FFN, 1024, wt + WT_2, t % 44, t / 44, smem); return; }
;   t -= WC_T_2;
;   wconv_tile<0>(p.rwkv_g2 + (size_t)l * 128 * 512, 128, 512, wt + WT_G2, t % 2, t / 2, smem);
; }
; DI void run_phase(const Params& p, int ph, int bid, int nb, char* smem) {
;     ...
;     if (nb >= 384) {
;       if (bid < 192) mods_item(p, bid, smem);
;       else for (int it = bid - 192; it < WC_TOTAL; it += nb - 192) wconv_item(p, 0, it, smem);
.LBB0_863:
	s_andn2_b64 vcc, exec, s[0:1]
	s_cbranch_vccnz .LBB0_909
	v_readlane_b32 s4, v246, 14
	v_readlane_b32 s5, v246, 15
	s_mov_b64 s[0:1], -1
	s_and_b64 vcc, exec, s[4:5]
	s_cbranch_vccz .LBB0_900
	v_readlane_b32 s0, v246, 16
	v_readlane_b32 s1, v246, 17
	s_andn2_b64 vcc, exec, s[0:1]
	s_cbranch_vccnz .LBB0_899
	v_writelane_b32 v255, s0, 0
	v_writelane_b32 v255, s1, 1
	v_writelane_b32 v255, s2, 2
	v_writelane_b32 v255, s3, 3
	v_writelane_b32 v255, s4, 4
	v_writelane_b32 v255, s5, 5
	v_writelane_b32 v255, s6, 6
	v_writelane_b32 v255, s7, 7
	v_writelane_b32 v255, s8, 8
	v_writelane_b32 v255, s9, 9
	v_writelane_b32 v255, s10, 10
	v_writelane_b32 v255, s11, 11
	v_writelane_b32 v255, s12, 12
	v_writelane_b32 v255, s13, 13
	v_writelane_b32 v255, s14, 14
	v_writelane_b32 v255, s15, 15
	v_writelane_b32 v255, s16, 16
	v_writelane_b32 v255, s17, 17
	v_writelane_b32 v255, s18, 18
	v_writelane_b32 v255, s19, 19
	v_writelane_b32 v255, s20, 20
	v_writelane_b32 v255, s21, 21
	v_writelane_b32 v255, s22, 22
	v_writelane_b32 v255, s23, 23
	v_writelane_b32 v255, s24, 24
	v_writelane_b32 v255, s25, 25
	v_writelane_b32 v255, s26, 26
	v_writelane_b32 v255, s27, 27
	v_writelane_b32 v255, s28, 28
	v_writelane_b32 v255, s29, 29
	v_writelane_b32 v255, s30, 30
	v_writelane_b32 v255, s31, 31
	v_writelane_b32 v255, s32, 32
	v_writelane_b32 v255, s33, 33
	v_writelane_b32 v255, s34, 34
	v_writelane_b32 v255, s35, 35
	v_writelane_b32 v255, s36, 36
	v_writelane_b32 v255, s37, 37
	v_writelane_b32 v255, s38, 38
	v_writelane_b32 v255, s39, 39
	v_writelane_b32 v255, s40, 40
	v_writelane_b32 v255, s41, 41
	v_writelane_b32 v255, s42, 42
	v_writelane_b32 v255, s43, 43
	v_writelane_b32 v255, s44, 44
	v_writelane_b32 v255, s45, 45
	v_writelane_b32 v255, s46, 46
	v_writelane_b32 v255, s47, 47
	v_writelane_b32 v255, s48, 48
	v_writelane_b32 v255, s49, 49
	v_writelane_b32 v255, s50, 50
	v_writelane_b32 v255, s51, 51
	v_writelane_b32 v255, s52, 52
	v_writelane_b32 v255, s53, 53
	v_writelane_b32 v255, s54, 54
	v_writelane_b32 v255, s55, 55
	v_writelane_b32 v255, s56, 56
	v_writelane_b32 v255, s57, 57
	v_writelane_b32 v255, s58, 58
	v_writelane_b32 v255, s59, 59
	v_writelane_b32 v255, s60, 60
	v_writelane_b32 v255, s61, 61
	v_writelane_b32 v255, s62, 62
	v_writelane_b32 v255, s63, 63
	v_writelane_b32 v254, s64, 0
	v_writelane_b32 v254, s65, 1
	v_writelane_b32 v254, s66, 2
	v_writelane_b32 v254, s67, 3
	v_writelane_b32 v254, s68, 4
	v_writelane_b32 v254, s69, 5
	v_writelane_b32 v254, s70, 6
	v_writelane_b32 v254, s71, 7
	v_writelane_b32 v254, s72, 8
	v_writelane_b32 v254, s73, 9
	v_writelane_b32 v254, s74, 10
	v_writelane_b32 v254, s75, 11
	v_writelane_b32 v254, s76, 12
	v_writelane_b32 v254, s77, 13
	v_writelane_b32 v254, s78, 14
	v_writelane_b32 v254, s79, 15
	v_writelane_b32 v254, s80, 16
	v_writelane_b32 v254, s81, 17
	v_writelane_b32 v254, s82, 18
	v_writelane_b32 v254, s83, 19
	v_writelane_b32 v254, s84, 20
	v_writelane_b32 v254, s85, 21
	v_readlane_b32 s4, v246, 4
	v_readlane_b32 s5, v246, 5
	v_readlane_b32 s22, v244, 54
	v_readlane_b32 s23, v243, 8
	s_sub_u32 s4, s4, 0xe8
	s_subb_u32 s5, s5, 0
	s_load_dwordx2 s[6:7], s[4:5], 0x40
	s_load_dwordx2 s[8:9], s[4:5], 0xa8
	s_load_dwordx2 s[10:11], s[4:5], 0xb0
	s_load_dwordx2 s[12:13], s[4:5], 0xb8
	s_load_dwordx2 s[14:15], s[4:5], 0xc0
	s_load_dwordx2 s[16:17], s[4:5], 0xc8
	s_load_dwordx2 s[18:19], s[4:5], 0x80
	s_load_dwordx2 s[20:21], s[4:5], 0xe0
	s_mov_b32 s24, 0
	s_sub_u32 s22, s22, 192
	s_sub_u32 s23, s23, 192
	v_and_b32_e32 v76, 0xff, v196
	v_lshrrev_b32_e32 v62, 4, v76
	v_and_b32_e32 v63, 15, v76
	v_lshrrev_b32_e32 v77, 2, v63
	v_and_b32_e32 v75, 3, v63
	v_lshlrev_b32_e32 v75, 4, v75
	v_cmp_eq_u32_e32 vcc, 1, v77
	s_nop 1
	v_cndmask_b32_e64 v64, 0, 1, vcc
	v_cmp_eq_u32_e32 vcc, 2, v77
	s_nop 1
	v_cndmask_b32_e64 v65, 0, 1, vcc
	v_cmp_eq_u32_e32 vcc, 3, v77
	s_nop 1
	v_cndmask_b32_e64 v66, 0, 1, vcc
	v_mul_u32_u24_e32 v67, 272, v62
	v_lshl_add_u32 v67, v63, 4, v67
	v_and_b32_e32 v69, 63, v76
	v_lshrrev_b32_e32 v77, 6, v76
	v_lshlrev_b32_e32 v70, 5, v77
	v_mul_u32_u24_e32 v68, 4352, v77
	v_lshl_add_u32 v68, v69, 2, v68
	s_waitcnt lgkmcnt(0)
	s_cmp_lt_u32 s22, 4528
	s_cbranch_scc0 .Lwc0_exit
; DI int ltid() { int t = __builtin_amdgcn_workitem_id_x(); asm volatile("" : "+v"(t)); return t; }
; template <int MAPK>
; DI void wconv_tile(const float* __restrict__ W, int K, int Nsrc, u16* __restrict__ Wt, int kt, int nt,
;                            char* smem) {
;   float* tile = (float*)smem;
;   const int tid = ltid();
;   const int n = tid & 63;
;   const int nd = nt * 64 + n;
;   const int src = (MAPK == 1) ? map_in(nd) : (MAPK == 2 ? map_13(nd) : nd);
;   __syncthreads();
; #pragma unroll
;   for (int i = 0; i < 16; ++i) {
;     int k = i * 4 + (tid >> 6);
;     tile[k * 65 + n] = W[(size_t)(kt * 64 + k) * Nsrc + src];
	s_barrier
	s_mov_b32 s46, 0
	s_mov_b32 s47, 1024
	s_mov_b32 s48, 7040
	s_mov_b32 s49, 0
	s_mov_b32 s50, 1
	s_mov_b32 s51, 0
	s_mov_b64 s[52:53], s[6:7]
	s_cmp_ge_u32 s22, 1760
	s_cselect_b32 s46, 1760, s46
	s_cselect_b32 s47, 1024, s47
	s_cselect_b32 s48, 1024, s48
	s_cselect_b32 s49, 7208960, s49
	s_cselect_b32 s50, 0, s50
	s_cselect_b32 s51, 1, s51
	s_cselect_b64 s[52:53], s[8:9], s[52:53]
	s_cmp_ge_u32 s22, 2016
	s_cselect_b32 s46, 2016, s46
	s_cselect_b32 s47, 512, s47
	s_cselect_b32 s48, 1024, s48
	s_cselect_b32 s49, 8257536, s49
	s_cselect_b32 s50, 0, s50
	s_cselect_b32 s51, 2, s51
	s_cselect_b64 s[52:53], s[10:11], s[52:53]
	s_cmp_ge_u32 s22, 2144
	s_cselect_b32 s46, 2144, s46
	s_cselect_b32 s47, 1024, s47
	s_cselect_b32 s48, 1024, s48
	s_cselect_b32 s49, 8781824, s49
	s_cselect_b32 s50, 0, s50
	s_cselect_b32 s51, 3, s51
	s_cselect_b64 s[52:53], s[12:13], s[52:53]
	s_cmp_ge_u32 s22, 2400
	s_cselect_b32 s46, 2400, s46
	s_cselect_b32 s47, 1024, s47
	s_cselect_b32 s48, 5632, s48
	s_cselect_b32 s49, 9830400, s49
	s_cselect_b32 s50, 2, s50
	s_cselect_b32 s51, 4, s51
	s_cselect_b64 s[52:53], s[14:15], s[52:53]
	s_cmp_ge_u32 s22, 3808
	s_cselect_b32 s46, 3808, s46
	s_cselect_b32 s47, 2816, s47
	s_cselect_b32 s48, 1024, s48
	s_cselect_b32 s49, 15597568, s49
	s_cselect_b32 s50, 0, s50
	s_cselect_b32 s51, 5, s51
	s_cselect_b64 s[52:53], s[16:17], s[52:53]
	s_cmp_ge_u32 s22, 4512
	s_cselect_b32 s46, 4512, s46
	s_cselect_b32 s47, 128, s47
	s_cselect_b32 s48, 512, s48
	s_cselect_b32 s49, 18481152, s49
	s_cselect_b32 s50, 0, s50
	s_cselect_b32 s51, 6, s51
	s_cselect_b64 s[52:53], s[18:19], s[52:53]
	s_sub_u32 s46, s22, s46
	s_mov_b32 s54, 9533
	s_mov_b32 s55, 110
	s_cmp_eq_u32 s51, 1
	s_cselect_b32 s54, 65536, s54
	s_cselect_b32 s55, 16, s55
	s_cmp_eq_u32 s51, 2
	s_cselect_b32 s54, 65536, s54
	s_cselect_b32 s55, 16, s55
	s_cmp_eq_u32 s51, 3
	s_cselect_b32 s54, 65536, s54
	s_cselect_b32 s55, 16, s55
	s_cmp_eq_u32 s51, 4
	s_cselect_b32 s54, 11916, s54
	s_cselect_b32 s55, 88, s55
	s_cmp_eq_u32 s51, 5
	s_cselect_b32 s54, 65536, s54
	s_cselect_b32 s55, 16, s55
	s_cmp_eq_u32 s51, 6
	s_cselect_b32 s54, 131072, s54
	s_cselect_b32 s55, 8, s55
	s_mul_i32 s56, s46, s54
	s_lshr_b32 s56, s56, 20
	s_mul_i32 s55, s56, s55
	s_sub_u32 s55, s46, s55
	s_lshl_b32 s28, s48, 2
	s_lshl_b32 s32, s47, 1
	s_mul_i32 s46, s47, s48
	s_mul_i32 s46, s46, s24
	s_lshl_b32 s57, s56, 6
	s_mul_i32 s57, s57, s48
	s_add_u32 s46, s46, s57
	s_lshl_b32 s46, s46, 2
	s_add_u32 s26, s52, s46
	s_addc_u32 s27, s53, 0
	s_lshl_b32 s46, s55, 6
	s_mul_i32 s46, s46, s47
	s_lshl_b32 s57, s56, 6
	s_add_u32 s46, s46, s57
	s_add_u32 s46, s46, s49
	s_lshl_b32 s46, s46, 1
	s_add_u32 s30, s20, s46
	s_addc_u32 s31, s21, 0
	s_lshl_b32 s46, s55, 8
	s_add_u32 s42, s46, 0
	s_add_u32 s43, s46, 64
	s_add_u32 s44, s46, 128
	s_add_u32 s45, s46, 192
	s_cmp_lt_u32 s55, 16
	s_cselect_b32 s57, 1, 0
	s_and_b32 s57, s57, s50
	s_cmp_eq_u32 s57, 1
	s_cselect_b32 s56, s44, s43
	s_cselect_b32 s44, s43, s44
	s_mov_b32 s43, s56
	s_lshl_b32 s46, s55, 7
	s_add_u32 s56, s46, 64
	s_add_u32 s57, s46, 11264
	s_cmp_eq_u32 s50, 2
	s_cselect_b32 s42, s46, s42
	s_cselect_b32 s43, s56, s43
	s_cselect_b32 s44, s57, s44
	s_add_u32 s57, s57, 64
	s_cmp_eq_u32 s50, 2
	s_cselect_b32 s45, s57, s45
	v_mul_u32_u24_e32 v71, s28, v62
	v_add_u32_e32 v71, s42, v71
	s_sub_u32 s46, s43, s42
	s_sub_u32 s47, s44, s42
	s_sub_u32 s48, s45, s42
	v_mad_u32_u24 v71, v64, s46, v71
	v_mad_u32_u24 v71, v65, s47, v71
	v_mad_u32_u24 v71, v66, s48, v71
	v_add_u32_e32 v71, v71, v75
	s_lshl_b32 s46, s28, 4
	s_mov_b64 s[58:59], s[26:27]
	s_add_u32 s60, s58, s46
	s_addc_u32 s61, s59, 0
	s_add_u32 s62, s60, s46
	s_addc_u32 s63, s61, 0
	s_add_u32 s64, s62, s46
	s_addc_u32 s65, s63, 0
	global_load_dwordx4 v[6:9], v71, s[58:59]
	global_load_dwordx4 v[10:13], v71, s[60:61]
	global_load_dwordx4 v[14:17], v71, s[62:63]
	global_load_dwordx4 v[18:21], v71, s[64:65]

; DI float siluf_(float x) { return x * frcp(1.f + __expf(-x)); }
; DI int ltid() { int t = __builtin_amdgcn_workitem_id_x(); asm volatile("" : "+v"(t)); return t; }
; DI void mods_item(const Params& p, int item, char* smem) {
;   const int l = item / 96, cg0 = (item % 96) * 64;
;   const int tid = ltid(), lane = tid & 63, wid = tid >> 6;
;   float acc[17];
; #pragma unroll
;   for (int b = 0; b < 17; ++b) acc[b] = 0.f;
;   const float* W = p.mod_w + (size_t)l * 1024 * 6144 + cg0 + lane;
;   for (int kb = 0; kb < 4; ++kb) {
;     const int k0 = wid * 256 + kb * 64;
;     float s[17];
; #pragma unroll
;     for (int b = 0; b < 17; ++b) {
;       float cv = (b < 16) ? p.c[b * 1024 + k0 + lane] : p.c_ctx[k0 + lane];
;       s[b] = siluf_(cv);
;     }
; #pragma unroll 8
;     for (int kk = 0; kk < 64; ++kk) {
;       float wv = W[(size_t)(k0 + kk) * 6144];
.LBB0_900:
	s_andn2_b64 vcc, exec, s[0:1]
	s_cbranch_vccnz .LBB0_909
	v_writelane_b32 v255, s0, 0
	v_writelane_b32 v255, s1, 1
	v_writelane_b32 v255, s2, 2
	v_writelane_b32 v255, s3, 3
	v_writelane_b32 v255, s4, 4
	v_writelane_b32 v255, s5, 5
	v_writelane_b32 v255, s6, 6
	v_writelane_b32 v255, s7, 7
	v_writelane_b32 v255, s8, 8
	v_writelane_b32 v255, s9, 9
	v_writelane_b32 v255, s10, 10
	v_writelane_b32 v255, s11, 11
	v_writelane_b32 v255, s12, 12
	v_writelane_b32 v255, s13, 13
	v_writelane_b32 v255, s14, 14
	v_writelane_b32 v255, s15, 15
	v_writelane_b32 v255, s16, 16
	v_writelane_b32 v255, s17, 17
	v_writelane_b32 v255, s18, 18
	v_writelane_b32 v255, s19, 19
	v_writelane_b32 v255, s20, 20
	v_writelane_b32 v255, s21, 21
	v_writelane_b32 v255, s22, 22
	v_writelane_b32 v255, s23, 23
	v_writelane_b32 v255, s24, 24
	v_writelane_b32 v255, s25, 25
	v_writelane_b32 v255, s26, 26
	v_writelane_b32 v255, s27, 27
	v_writelane_b32 v255, s28, 28
	v_writelane_b32 v255, s29, 29
	v_writelane_b32 v255, s30, 30
	v_writelane_b32 v255, s31, 31
	v_writelane_b32 v255, s32, 32
	v_writelane_b32 v255, s33, 33
	v_writelane_b32 v255, s34, 34
	v_writelane_b32 v255, s35, 35
	v_writelane_b32 v255, s36, 36
	v_writelane_b32 v255, s37, 37
	v_writelane_b32 v255, s38, 38
	v_writelane_b32 v255, s39, 39
	v_writelane_b32 v255, s40, 40
	v_writelane_b32 v255, s41, 41
	v_writelane_b32 v255, s42, 42
	v_writelane_b32 v255, s43, 43
	v_writelane_b32 v255, s44, 44
	v_writelane_b32 v255, s45, 45
	v_writelane_b32 v255, s46, 46
	v_writelane_b32 v255, s47, 47
	v_writelane_b32 v255, s48, 48
	v_writelane_b32 v255, s49, 49
	v_readlane_b32 s4, v246, 4
	v_readlane_b32 s5, v246, 5
	v_readlane_b32 s16, v244, 54
	s_sub_u32 s4, s4, 0xe8
	s_subb_u32 s5, s5, 0
	s_load_dwordx2 s[6:7], s[4:5], 0x8
	s_load_dwordx2 s[8:9], s[4:5], 0x18
	s_load_dwordx2 s[10:11], s[4:5], 0x20
	s_load_dwordx2 s[12:13], s[4:5], 0x28
	s_load_dwordx2 s[14:15], s[4:5], 0xe0
	s_cmp_ge_u32 s16, 96
	s_cselect_b32 s17, 1, 0
	s_mul_i32 s26, s17, 96
	s_sub_u32 s18, s16, s26
	s_lshl_b32 s18, s18, 6
	v_and_b32_e32 v106, 63, v196
	v_lshlrev_b32_e32 v111, 2, v106
	v_lshrrev_b32_e32 v107, 6, v196
	s_nop 0
	v_readfirstlane_b32 s19, v107
	v_mov_b32_e32 v6, 0
	v_mov_b32_e32 v7, 0
	v_mov_b32_e32 v8, 0
	v_mov_b32_e32 v9, 0
	v_mov_b32_e32 v10, 0
	v_mov_b32_e32 v11, 0
	v_mov_b32_e32 v12, 0
	v_mov_b32_e32 v13, 0
	v_mov_b32_e32 v14, 0
	v_mov_b32_e32 v15, 0
	v_mov_b32_e32 v16, 0
	v_mov_b32_e32 v17, 0
	v_mov_b32_e32 v18, 0
	v_mov_b32_e32 v19, 0
	v_mov_b32_e32 v20, 0
	v_mov_b32_e32 v21, 0
	v_mov_b32_e32 v22, 0
	s_waitcnt lgkmcnt(0)
	s_lshl_b32 s26, s17, 10
	s_lshl_b32 s27, s19, 8
	s_add_u32 s26, s26, s27
	s_mul_i32 s27, s26, 24576
	s_mul_hi_u32 s28, s26, 24576
	s_lshl_b32 s29, s18, 2
	s_add_u32 s27, s27, s29
	s_addc_u32 s28, s28, 0
	s_add_u32 s22, s10, s27
	s_addc_u32 s23, s11, s28
	s_lshl_b32 s26, s19, 10
	s_add_u32 s24, s6, s26
	s_addc_u32 s25, s7, 0
	s_add_u32 s8, s8, s26
	s_addc_u32 s9, s9, 0
	s_mov_b32 s20, 0
.Lmods_kb:
	s_mov_b64 s[26:27], s[24:25]
	global_load_dword v24, v111, s[26:27]
	s_add_u32 s26, s26, 0x1000
	s_addc_u32 s27, s27, 0
	global_load_dword v25, v111, s[26:27]
	s_add_u32 s26, s26, 0x1000
	s_addc_u32 s27, s27, 0
	global_load_dword v26, v111, s[26:27]
	s_add_u32 s26, s26, 0x1000
	s_addc_u32 s27, s27, 0
	global_load_dword v27, v111, s[26:27]
	s_add_u32 s26, s26, 0x1000
	s_addc_u32 s27, s27, 0
	global_load_dword v28, v111, s[26:27]
	s_add_u32 s26, s26, 0x1000
	s_addc_u32 s27, s27, 0
	global_load_dword v29, v111, s[26:27]
	s_add_u32 s26, s26, 0x1000
	s_addc_u32 s27, s27, 0
	global_load_dword v30, v111, s[26:27]
	s_add_u32 s26, s26, 0x1000
	s_addc_u32 s27, s27, 0
	global_load_dword v31, v111, s[26:27]
	s_add_u32 s26, s26, 0x1000
	s_addc_u32 s27, s27, 0
	global_load_dword v32, v111, s[26:27]
	s_add_u32 s26, s26, 0x1000
	s_addc_u32 s27, s27, 0
	global_load_dword v33, v111, s[26:27]
	s_add_u32 s26, s26, 0x1000
	s_addc_u32 s27, s27, 0
	global_load_dword v34, v111, s[26:27]
	s_add_u32 s26, s26, 0x1000
	s_addc_u32 s27, s27, 0
	global_load_dword v35, v111, s[26:27]
	s_add_u32 s26, s26, 0x1000
	s_addc_u32 s27, s27, 0
	global_load_dword v36, v111, s[26:27]
	s_add_u32 s26, s26, 0x1000
	s_addc_u32 s27, s27, 0
	global_load_dword v37, v111, s[26:27]
	s_add_u32 s26, s26, 0x1000
	s_addc_u32 s27, s27, 0
	global_load_dword v38, v111, s[26:27]
	s_add_u32 s26, s26, 0x1000
	s_addc_u32 s27, s27, 0
	global_load_dword v39, v111, s[26:27]
	s_add_u32 s26, s26, 0x1000
	s_addc_u32 s27, s27, 0
	global_load_dword v40, v111, s[8:9]
	global_load_dword v42, v111, s[22:23]
	s_add_u32 s22, s22, 24576
	s_addc_u32 s23, s23, 0
	global_load_dword v43, v111, s[22:23]
	s_add_u32 s22, s22, 24576
	s_addc_u32 s23, s23, 0
	global_load_dword v44, v111, s[22:23]
	s_add_u32 s22, s22, 24576
	s_addc_u32 s23, s23, 0
	global_load_dword v45, v111, s[22:23]
	s_add_u32 s22, s22, 24576
	s_addc_u32 s23, s23, 0
	global_load_dword v46, v111, s[22:23]
	s_add_u32 s22, s22, 24576
	s_addc_u32 s23, s23, 0
	global_load_dword v47, v111, s[22:23]
	s_add_u32 s22, s22, 24576
	s_addc_u32 s23, s23, 0
	global_load_dword v48, v111, s[22:23]
	s_add_u32 s22, s22, 24576
	s_addc_u32 s23, s23, 0
	global_load_dword v49, v111, s[22:23]
	s_add_u32 s22, s22, 24576
	s_addc_u32 s23, s23, 0
	global_load_dword v50, v111, s[22:23]
	s_add_u32 s22, s22, 24576
	s_addc_u32 s23, s23, 0
	global_load_dword v51, v111, s[22:23]
	s_add_u32 s22, s22, 24576
	s_addc_u32 s23, s23, 0
	global_load_dword v52, v111, s[22:23]
	s_add_u32 s22, s22, 24576
	s_addc_u32 s23, s23, 0
	global_load_dword v53, v111, s[22:23]
	s_add_u32 s22, s22, 24576
	s_addc_u32 s23, s23, 0
	global_load_dword v54, v111, s[22:23]
	s_add_u32 s22, s22, 24576
; DI float siluf_(float x) { return x * frcp(1.f + __expf(-x)); }
; DI void mods_item(const Params& p, int item, char* smem) {
;     ...
;     float s[17];
; #pragma unroll
;     for (int b = 0; b < 17; ++b) {
;       float cv = (b < 16) ? p.c[b * 1024 + k0 + lane] : p.c_ctx[k0 + lane];
;       s[b] = siluf_(cv);
;     }
; #pragma unroll 8
;     for (int kk = 0; kk < 64; ++kk) {
;       float wv = W[(size_t)(k0 + kk) * 6144];
; #pragma unroll
;       for (int b = 0; b < 17; ++b) acc[b] += __shfl(s[b], kk, 64) * wv;
	s_addc_u32 s23, s23, 0
	global_load_dword v55, v111, s[22:23]
	s_add_u32 s22, s22, 24576
	s_addc_u32 s23, s23, 0
	global_load_dword v56, v111, s[22:23]
	s_add_u32 s22, s22, 24576
	s_addc_u32 s23, s23, 0
	global_load_dword v57, v111, s[22:23]
	s_add_u32 s22, s22, 24576
	s_addc_u32 s23, s23, 0
	global_load_dword v58, v111, s[22:23]
	s_add_u32 s22, s22, 24576
	s_addc_u32 s23, s23, 0
	global_load_dword v59, v111, s[22:23]
	s_add_u32 s22, s22, 24576
	s_addc_u32 s23, s23, 0
	global_load_dword v60, v111, s[22:23]
	s_add_u32 s22, s22, 24576
	s_addc_u32 s23, s23, 0
	global_load_dword v61, v111, s[22:23]
	s_add_u32 s22, s22, 24576
	s_addc_u32 s23, s23, 0
	global_load_dword v62, v111, s[22:23]
	s_add_u32 s22, s22, 24576
	s_addc_u32 s23, s23, 0
	global_load_dword v63, v111, s[22:23]
	s_add_u32 s22, s22, 24576
	s_addc_u32 s23, s23, 0
	global_load_dword v64, v111, s[22:23]
	s_add_u32 s22, s22, 24576
	s_addc_u32 s23, s23, 0
	global_load_dword v65, v111, s[22:23]
	s_add_u32 s22, s22, 24576
	s_addc_u32 s23, s23, 0
	global_load_dword v66, v111, s[22:23]
	s_add_u32 s22, s22, 24576
	s_addc_u32 s23, s23, 0
	global_load_dword v67, v111, s[22:23]
	s_add_u32 s22, s22, 24576
	s_addc_u32 s23, s23, 0
	global_load_dword v68, v111, s[22:23]
	s_add_u32 s22, s22, 24576
	s_addc_u32 s23, s23, 0
	global_load_dword v69, v111, s[22:23]
	s_add_u32 s22, s22, 24576
	s_addc_u32 s23, s23, 0
	global_load_dword v70, v111, s[22:23]
	s_add_u32 s22, s22, 24576
	s_addc_u32 s23, s23, 0
	global_load_dword v71, v111, s[22:23]
	s_add_u32 s22, s22, 24576
	s_addc_u32 s23, s23, 0
	global_load_dword v72, v111, s[22:23]
	s_add_u32 s22, s22, 24576
	s_addc_u32 s23, s23, 0
	global_load_dword v73, v111, s[22:23]
	s_add_u32 s22, s22, 24576
	s_addc_u32 s23, s23, 0
	global_load_dword v74, v111, s[22:23]
	s_add_u32 s22, s22, 24576
	s_addc_u32 s23, s23, 0
	global_load_dword v75, v111, s[22:23]
	s_add_u32 s22, s22, 24576
	s_addc_u32 s23, s23, 0
	global_load_dword v76, v111, s[22:23]
	s_add_u32 s22, s22, 24576
	s_addc_u32 s23, s23, 0
	global_load_dword v77, v111, s[22:23]
	s_add_u32 s22, s22, 24576
	s_addc_u32 s23, s23, 0
	global_load_dword v78, v111, s[22:23]
	s_add_u32 s22, s22, 24576
	s_addc_u32 s23, s23, 0
	global_load_dword v79, v111, s[22:23]
	s_add_u32 s22, s22, 24576
	s_addc_u32 s23, s23, 0
	global_load_dword v80, v111, s[22:23]
	s_add_u32 s22, s22, 24576
	s_addc_u32 s23, s23, 0
	global_load_dword v81, v111, s[22:23]
	s_add_u32 s22, s22, 24576
	s_addc_u32 s23, s23, 0
	global_load_dword v82, v111, s[22:23]
	s_add_u32 s22, s22, 24576
	s_addc_u32 s23, s23, 0
	global_load_dword v83, v111, s[22:23]
	s_add_u32 s22, s22, 24576
	s_addc_u32 s23, s23, 0
	global_load_dword v84, v111, s[22:23]
	s_add_u32 s22, s22, 24576
	s_addc_u32 s23, s23, 0
	global_load_dword v85, v111, s[22:23]
	s_add_u32 s22, s22, 24576
	s_addc_u32 s23, s23, 0
	global_load_dword v86, v111, s[22:23]
	s_add_u32 s22, s22, 24576
	s_addc_u32 s23, s23, 0
	global_load_dword v87, v111, s[22:23]
	s_add_u32 s22, s22, 24576
	s_addc_u32 s23, s23, 0
	s_waitcnt vmcnt(46)
	v_mul_f32_e32 v88, 0xbfb8aa3b, v24
	v_mul_f32_e32 v89, 0xbfb8aa3b, v25
	v_mul_f32_e32 v90, 0xbfb8aa3b, v26
	v_mul_f32_e32 v91, 0xbfb8aa3b, v27
	v_mul_f32_e32 v92, 0xbfb8aa3b, v28
	v_mul_f32_e32 v93, 0xbfb8aa3b, v29
	v_mul_f32_e32 v94, 0xbfb8aa3b, v30
	v_mul_f32_e32 v95, 0xbfb8aa3b, v31
	v_mul_f32_e32 v96, 0xbfb8aa3b, v32
	v_mul_f32_e32 v97, 0xbfb8aa3b, v33
	v_mul_f32_e32 v98, 0xbfb8aa3b, v34
	v_mul_f32_e32 v99, 0xbfb8aa3b, v35
	v_mul_f32_e32 v100, 0xbfb8aa3b, v36
	v_mul_f32_e32 v101, 0xbfb8aa3b, v37
	v_mul_f32_e32 v102, 0xbfb8aa3b, v38
	v_mul_f32_e32 v103, 0xbfb8aa3b, v39
	v_mul_f32_e32 v104, 0xbfb8aa3b, v40
	v_exp_f32_e32 v88, v88
	v_exp_f32_e32 v89, v89
	v_exp_f32_e32 v90, v90
	v_exp_f32_e32 v91, v91
	v_exp_f32_e32 v92, v92
	v_exp_f32_e32 v93, v93
	v_exp_f32_e32 v94, v94
	v_exp_f32_e32 v95, v95
	v_exp_f32_e32 v96, v96
	v_exp_f32_e32 v97, v97
	v_exp_f32_e32 v98, v98
	v_exp_f32_e32 v99, v99
	v_exp_f32_e32 v100, v100
	v_exp_f32_e32 v101, v101
	v_exp_f32_e32 v102, v102
	v_exp_f32_e32 v103, v103
	v_exp_f32_e32 v104, v104
	s_nop 0
	v_add_f32_e32 v88, 1.0, v88
	v_add_f32_e32 v89, 1.0, v89
	v_add_f32_e32 v90, 1.0, v90
	v_add_f32_e32 v91, 1.0, v91
	v_add_f32_e32 v92, 1.0, v92
	v_add_f32_e32 v93, 1.0, v93
	v_add_f32_e32 v94, 1.0, v94
	v_add_f32_e32 v95, 1.0, v95
	v_add_f32_e32 v96, 1.0, v96
	v_add_f32_e32 v97, 1.0, v97
	v_add_f32_e32 v98, 1.0, v98
	v_add_f32_e32 v99, 1.0, v99
	v_add_f32_e32 v100, 1.0, v100
	v_add_f32_e32 v101, 1.0, v101
	v_add_f32_e32 v102, 1.0, v102
	v_add_f32_e32 v103, 1.0, v103
	v_add_f32_e32 v104, 1.0, v104
	v_rcp_f32_e32 v88, v88
	v_rcp_f32_e32 v89, v89
	v_rcp_f32_e32 v90, v90
	v_rcp_f32_e32 v91, v91
	v_rcp_f32_e32 v92, v92
	v_rcp_f32_e32 v93, v93
	v_rcp_f32_e32 v94, v94
	v_rcp_f32_e32 v95, v95
	v_rcp_f32_e32 v96, v96
	v_rcp_f32_e32 v97, v97
	v_rcp_f32_e32 v98, v98
	v_rcp_f32_e32 v99, v99
	v_rcp_f32_e32 v100, v100
	v_rcp_f32_e32 v101, v101
	v_rcp_f32_e32 v102, v102
	v_rcp_f32_e32 v103, v103
	v_rcp_f32_e32 v104, v104
	s_nop 0
	v_mul_f32_e32 v24, v24, v88
	v_mul_f32_e32 v25, v25, v89
	v_mul_f32_e32 v26, v26, v90
	v_mul_f32_e32 v27, v27, v91
	v_mul_f32_e32 v28, v28, v92
	v_mul_f32_e32 v29, v29, v93
	v_mul_f32_e32 v30, v30, v94
	v_mul_f32_e32 v31, v31, v95
	v_mul_f32_e32 v32, v32, v96
	v_mul_f32_e32 v33, v33, v97
	v_mul_f32_e32 v34, v34, v98
	v_mul_f32_e32 v35, v35, v99
	v_mul_f32_e32 v36, v36, v100
	v_mul_f32_e32 v37, v37, v101
	v_mul_f32_e32 v38, v38, v102
	v_mul_f32_e32 v39, v39, v103
	v_mul_f32_e32 v40, v40, v104
	s_waitcnt vmcnt(45)
; DI void mods_item(const Params& p, int item, char* smem) {
;     ...
; #pragma unroll 8
;     for (int kk = 0; kk < 64; ++kk) {
;       float wv = W[(size_t)(k0 + kk) * 6144];
; #pragma unroll
;       for (int b = 0; b < 17; ++b) acc[b] += __shfl(s[b], kk, 64) * wv;
;     }
	global_load_dword v88, v111, s[22:23]
	s_add_u32 s22, s22, 24576
	s_addc_u32 s23, s23, 0
	global_load_dword v89, v111, s[22:23]
	s_add_u32 s22, s22, 24576
	s_addc_u32 s23, s23, 0
	global_load_dword v90, v111, s[22:23]
	s_add_u32 s22, s22, 24576
	s_addc_u32 s23, s23, 0
	global_load_dword v91, v111, s[22:23]
	s_add_u32 s22, s22, 24576
	s_addc_u32 s23, s23, 0
	global_load_dword v92, v111, s[22:23]
	s_add_u32 s22, s22, 24576
	s_addc_u32 s23, s23, 0
	global_load_dword v93, v111, s[22:23]
	s_add_u32 s22, s22, 24576
	s_addc_u32 s23, s23, 0
	global_load_dword v94, v111, s[22:23]
	s_add_u32 s22, s22, 24576
	s_addc_u32 s23, s23, 0
	global_load_dword v95, v111, s[22:23]
	s_add_u32 s22, s22, 24576
	s_addc_u32 s23, s23, 0
	global_load_dword v96, v111, s[22:23]
	s_add_u32 s22, s22, 24576
	s_addc_u32 s23, s23, 0
	global_load_dword v97, v111, s[22:23]
	s_add_u32 s22, s22, 24576
	s_addc_u32 s23, s23, 0
	global_load_dword v98, v111, s[22:23]
	s_add_u32 s22, s22, 24576
	s_addc_u32 s23, s23, 0
	global_load_dword v99, v111, s[22:23]
	s_add_u32 s22, s22, 24576
	s_addc_u32 s23, s23, 0
	global_load_dword v100, v111, s[22:23]
	s_add_u32 s22, s22, 24576
	s_addc_u32 s23, s23, 0
	global_load_dword v101, v111, s[22:23]
	s_add_u32 s22, s22, 24576
	s_addc_u32 s23, s23, 0
	global_load_dword v102, v111, s[22:23]
	s_add_u32 s22, s22, 24576
	s_addc_u32 s23, s23, 0
	global_load_dword v103, v111, s[22:23]
	s_add_u32 s22, s22, 24576
	s_addc_u32 s23, s23, 0
	global_load_dword v104, v111, s[22:23]
	s_add_u32 s22, s22, 24576
	s_addc_u32 s23, s23, 0
	global_load_dword v105, v111, s[22:23]
	s_add_u32 s22, s22, 24576
	s_addc_u32 s23, s23, 0
	s_waitcnt vmcnt(63)
	v_readlane_b32 s32, v24, 0
	v_readlane_b32 s33, v25, 0
	v_readlane_b32 s34, v26, 0
	v_readlane_b32 s35, v27, 0
	v_readlane_b32 s36, v28, 0
	v_readlane_b32 s37, v29, 0
	v_readlane_b32 s38, v30, 0
	v_readlane_b32 s39, v31, 0
	v_readlane_b32 s40, v32, 0
	v_readlane_b32 s41, v33, 0
	v_readlane_b32 s42, v34, 0
	v_readlane_b32 s43, v35, 0
	v_readlane_b32 s44, v36, 0
	v_readlane_b32 s45, v37, 0
	v_readlane_b32 s46, v38, 0
	v_readlane_b32 s47, v39, 0
	v_readlane_b32 s48, v40, 0
	v_fmac_f32_e32 v6, s32, v42
	v_fmac_f32_e32 v7, s33, v42
	v_fmac_f32_e32 v8, s34, v42
	v_fmac_f32_e32 v9, s35, v42
	v_fmac_f32_e32 v10, s36, v42
	v_fmac_f32_e32 v11, s37, v42
	v_fmac_f32_e32 v12, s38, v42
	v_fmac_f32_e32 v13, s39, v42
	v_fmac_f32_e32 v14, s40, v42
	v_fmac_f32_e32 v15, s41, v42
	v_fmac_f32_e32 v16, s42, v42
	v_fmac_f32_e32 v17, s43, v42
	v_fmac_f32_e32 v18, s44, v42
	v_fmac_f32_e32 v19, s45, v42
	v_fmac_f32_e32 v20, s46, v42
	v_fmac_f32_e32 v21, s47, v42
	v_fmac_f32_e32 v22, s48, v42
	s_waitcnt vmcnt(62)
	v_readlane_b32 s32, v24, 1
	v_readlane_b32 s33, v25, 1
	v_readlane_b32 s34, v26, 1
	v_readlane_b32 s35, v27, 1
	v_readlane_b32 s36, v28, 1
	v_readlane_b32 s37, v29, 1
	v_readlane_b32 s38, v30, 1
	v_readlane_b32 s39, v31, 1
	v_readlane_b32 s40, v32, 1
	v_readlane_b32 s41, v33, 1
	v_readlane_b32 s42, v34, 1
	v_readlane_b32 s43, v35, 1
	v_readlane_b32 s44, v36, 1
	v_readlane_b32 s45, v37, 1
	v_readlane_b32 s46, v38, 1
	v_readlane_b32 s47, v39, 1
	v_readlane_b32 s48, v40, 1
	v_fmac_f32_e32 v6, s32, v43
	v_fmac_f32_e32 v7, s33, v43
	v_fmac_f32_e32 v8, s34, v43
	v_fmac_f32_e32 v9, s35, v43
	v_fmac_f32_e32 v10, s36, v43
	v_fmac_f32_e32 v11, s37, v43
	v_fmac_f32_e32 v12, s38, v43
	v_fmac_f32_e32 v13, s39, v43
	v_fmac_f32_e32 v14, s40, v43
	v_fmac_f32_e32 v15, s41, v43
	v_fmac_f32_e32 v16, s42, v43
	v_fmac_f32_e32 v17, s43, v43
	v_fmac_f32_e32 v18, s44, v43
	v_fmac_f32_e32 v19, s45, v43
	v_fmac_f32_e32 v20, s46, v43
	v_fmac_f32_e32 v21, s47, v43
	v_fmac_f32_e32 v22, s48, v43
	s_waitcnt vmcnt(61)
	v_readlane_b32 s32, v24, 2
	v_readlane_b32 s33, v25, 2
	v_readlane_b32 s34, v26, 2
	v_readlane_b32 s35, v27, 2
	v_readlane_b32 s36, v28, 2
	v_readlane_b32 s37, v29, 2
	v_readlane_b32 s38, v30, 2
	v_readlane_b32 s39, v31, 2
	v_readlane_b32 s40, v32, 2
	v_readlane_b32 s41, v33, 2
	v_readlane_b32 s42, v34, 2
	v_readlane_b32 s43, v35, 2
	v_readlane_b32 s44, v36, 2
	v_readlane_b32 s45, v37, 2
	v_readlane_b32 s46, v38, 2
	v_readlane_b32 s47, v39, 2
	v_readlane_b32 s48, v40, 2
	v_fmac_f32_e32 v6, s32, v44
	v_fmac_f32_e32 v7, s33, v44
	v_fmac_f32_e32 v8, s34, v44
	v_fmac_f32_e32 v9, s35, v44
	v_fmac_f32_e32 v10, s36, v44
	v_fmac_f32_e32 v11, s37, v44
	v_fmac_f32_e32 v12, s38, v44
	v_fmac_f32_e32 v13, s39, v44
	v_fmac_f32_e32 v14, s40, v44
	v_fmac_f32_e32 v15, s41, v44
	v_fmac_f32_e32 v16, s42, v44
	v_fmac_f32_e32 v17, s43, v44
	v_fmac_f32_e32 v18, s44, v44
	v_fmac_f32_e32 v19, s45, v44
	v_fmac_f32_e32 v20, s46, v44
	v_fmac_f32_e32 v21, s47, v44
	v_fmac_f32_e32 v22, s48, v44
	s_waitcnt vmcnt(60)
	v_readlane_b32 s32, v24, 3
	v_readlane_b32 s33, v25, 3
	v_readlane_b32 s34, v26, 3
	v_readlane_b32 s35, v27, 3
	v_readlane_b32 s36, v28, 3
	v_readlane_b32 s37, v29, 3
	v_readlane_b32 s38, v30, 3
	v_readlane_b32 s39, v31, 3
	v_readlane_b32 s40, v32, 3
	v_readlane_b32 s41, v33, 3
	v_readlane_b32 s42, v34, 3
	v_readlane_b32 s43, v35, 3
	v_readlane_b32 s44, v36, 3
	v_readlane_b32 s45, v37, 3
	v_readlane_b32 s46, v38, 3
	v_readlane_b32 s47, v39, 3
	v_readlane_b32 s48, v40, 3
	v_fmac_f32_e32 v6, s32, v45
	v_fmac_f32_e32 v7, s33, v45
	v_fmac_f32_e32 v8, s34, v45
	v_fmac_f32_e32 v9, s35, v45
	v_fmac_f32_e32 v10, s36, v45
	v_fmac_f32_e32 v11, s37, v45
	v_fmac_f32_e32 v12, s38, v45
	v_fmac_f32_e32 v13, s39, v45
	v_fmac_f32_e32 v14, s40, v45
	v_fmac_f32_e32 v15, s41, v45
	v_fmac_f32_e32 v16, s42, v45
	v_fmac_f32_e32 v17, s43, v45
	v_fmac_f32_e32 v18, s44, v45
	v_fmac_f32_e32 v19, s45, v45
	v_fmac_f32_e32 v20, s46, v45
	v_fmac_f32_e32 v21, s47, v45
	v_fmac_f32_e32 v22, s48, v45
	s_waitcnt vmcnt(59)
; DI void mods_item(const Params& p, int item, char* smem) {
;     ...
; #pragma unroll 8
;     for (int kk = 0; kk < 64; ++kk) {
;       float wv = W[(size_t)(k0 + kk) * 6144];
; #pragma unroll
;       for (int b = 0; b < 17; ++b) acc[b] += __shfl(s[b], kk, 64) * wv;
;     }
	v_readlane_b32 s32, v24, 4
	v_readlane_b32 s33, v25, 4
	v_readlane_b32 s34, v26, 4
	v_readlane_b32 s35, v27, 4
	v_readlane_b32 s36, v28, 4
	v_readlane_b32 s37, v29, 4
	v_readlane_b32 s38, v30, 4
	v_readlane_b32 s39, v31, 4
	v_readlane_b32 s40, v32, 4
	v_readlane_b32 s41, v33, 4
	v_readlane_b32 s42, v34, 4
	v_readlane_b32 s43, v35, 4
	v_readlane_b32 s44, v36, 4
	v_readlane_b32 s45, v37, 4
	v_readlane_b32 s46, v38, 4
	v_readlane_b32 s47, v39, 4
	v_readlane_b32 s48, v40, 4
	v_fmac_f32_e32 v6, s32, v46
	v_fmac_f32_e32 v7, s33, v46
	v_fmac_f32_e32 v8, s34, v46
	v_fmac_f32_e32 v9, s35, v46
	v_fmac_f32_e32 v10, s36, v46
	v_fmac_f32_e32 v11, s37, v46
	v_fmac_f32_e32 v12, s38, v46
	v_fmac_f32_e32 v13, s39, v46
	v_fmac_f32_e32 v14, s40, v46
	v_fmac_f32_e32 v15, s41, v46
	v_fmac_f32_e32 v16, s42, v46
	v_fmac_f32_e32 v17, s43, v46
	v_fmac_f32_e32 v18, s44, v46
	v_fmac_f32_e32 v19, s45, v46
	v_fmac_f32_e32 v20, s46, v46
	v_fmac_f32_e32 v21, s47, v46
	v_fmac_f32_e32 v22, s48, v46
	s_waitcnt vmcnt(58)
	v_readlane_b32 s32, v24, 5
	v_readlane_b32 s33, v25, 5
	v_readlane_b32 s34, v26, 5
	v_readlane_b32 s35, v27, 5
	v_readlane_b32 s36, v28, 5
	v_readlane_b32 s37, v29, 5
	v_readlane_b32 s38, v30, 5
	v_readlane_b32 s39, v31, 5
	v_readlane_b32 s40, v32, 5
	v_readlane_b32 s41, v33, 5
	v_readlane_b32 s42, v34, 5
	v_readlane_b32 s43, v35, 5
	v_readlane_b32 s44, v36, 5
	v_readlane_b32 s45, v37, 5
	v_readlane_b32 s46, v38, 5
	v_readlane_b32 s47, v39, 5
	v_readlane_b32 s48, v40, 5
	v_fmac_f32_e32 v6, s32, v47
	v_fmac_f32_e32 v7, s33, v47
	v_fmac_f32_e32 v8, s34, v47
	v_fmac_f32_e32 v9, s35, v47
	v_fmac_f32_e32 v10, s36, v47
	v_fmac_f32_e32 v11, s37, v47
	v_fmac_f32_e32 v12, s38, v47
	v_fmac_f32_e32 v13, s39, v47
	v_fmac_f32_e32 v14, s40, v47
	v_fmac_f32_e32 v15, s41, v47
	v_fmac_f32_e32 v16, s42, v47
	v_fmac_f32_e32 v17, s43, v47
	v_fmac_f32_e32 v18, s44, v47
	v_fmac_f32_e32 v19, s45, v47
	v_fmac_f32_e32 v20, s46, v47
	v_fmac_f32_e32 v21, s47, v47
	v_fmac_f32_e32 v22, s48, v47
	s_waitcnt vmcnt(57)
	v_readlane_b32 s32, v24, 6
	v_readlane_b32 s33, v25, 6
	v_readlane_b32 s34, v26, 6
	v_readlane_b32 s35, v27, 6
	v_readlane_b32 s36, v28, 6
	v_readlane_b32 s37, v29, 6
	v_readlane_b32 s38, v30, 6
	v_readlane_b32 s39, v31, 6
	v_readlane_b32 s40, v32, 6
	v_readlane_b32 s41, v33, 6
	v_readlane_b32 s42, v34, 6
	v_readlane_b32 s43, v35, 6
	v_readlane_b32 s44, v36, 6
	v_readlane_b32 s45, v37, 6
	v_readlane_b32 s46, v38, 6
	v_readlane_b32 s47, v39, 6
	v_readlane_b32 s48, v40, 6
	v_fmac_f32_e32 v6, s32, v48
	v_fmac_f32_e32 v7, s33, v48
	v_fmac_f32_e32 v8, s34, v48
	v_fmac_f32_e32 v9, s35, v48
	v_fmac_f32_e32 v10, s36, v48
	v_fmac_f32_e32 v11, s37, v48
	v_fmac_f32_e32 v12, s38, v48
	v_fmac_f32_e32 v13, s39, v48
	v_fmac_f32_e32 v14, s40, v48
	v_fmac_f32_e32 v15, s41, v48
	v_fmac_f32_e32 v16, s42, v48
	v_fmac_f32_e32 v17, s43, v48
	v_fmac_f32_e32 v18, s44, v48
	v_fmac_f32_e32 v19, s45, v48
	v_fmac_f32_e32 v20, s46, v48
	v_fmac_f32_e32 v21, s47, v48
	v_fmac_f32_e32 v22, s48, v48
	s_waitcnt vmcnt(56)
	v_readlane_b32 s32, v24, 7
	v_readlane_b32 s33, v25, 7
	v_readlane_b32 s34, v26, 7
	v_readlane_b32 s35, v27, 7
	v_readlane_b32 s36, v28, 7
	v_readlane_b32 s37, v29, 7
	v_readlane_b32 s38, v30, 7
	v_readlane_b32 s39, v31, 7
	v_readlane_b32 s40, v32, 7
	v_readlane_b32 s41, v33, 7
	v_readlane_b32 s42, v34, 7
	v_readlane_b32 s43, v35, 7
	v_readlane_b32 s44, v36, 7
	v_readlane_b32 s45, v37, 7
	v_readlane_b32 s46, v38, 7
	v_readlane_b32 s47, v39, 7
	v_readlane_b32 s48, v40, 7
	v_fmac_f32_e32 v6, s32, v49
	v_fmac_f32_e32 v7, s33, v49
	v_fmac_f32_e32 v8, s34, v49
	v_fmac_f32_e32 v9, s35, v49
	v_fmac_f32_e32 v10, s36, v49
	v_fmac_f32_e32 v11, s37, v49
	v_fmac_f32_e32 v12, s38, v49
	v_fmac_f32_e32 v13, s39, v49
	v_fmac_f32_e32 v14, s40, v49
	v_fmac_f32_e32 v15, s41, v49
	v_fmac_f32_e32 v16, s42, v49
	v_fmac_f32_e32 v17, s43, v49
	v_fmac_f32_e32 v18, s44, v49
	v_fmac_f32_e32 v19, s45, v49
	v_fmac_f32_e32 v20, s46, v49
	v_fmac_f32_e32 v21, s47, v49
	v_fmac_f32_e32 v22, s48, v49
	s_waitcnt vmcnt(55)
	v_readlane_b32 s32, v24, 8
	v_readlane_b32 s33, v25, 8
	v_readlane_b32 s34, v26, 8
	v_readlane_b32 s35, v27, 8
	v_readlane_b32 s36, v28, 8
	v_readlane_b32 s37, v29, 8
	v_readlane_b32 s38, v30, 8
	v_readlane_b32 s39, v31, 8
	v_readlane_b32 s40, v32, 8
	v_readlane_b32 s41, v33, 8
	v_readlane_b32 s42, v34, 8
	v_readlane_b32 s43, v35, 8
	v_readlane_b32 s44, v36, 8
	v_readlane_b32 s45, v37, 8
	v_readlane_b32 s46, v38, 8
	v_readlane_b32 s47, v39, 8
	v_readlane_b32 s48, v40, 8
	v_fmac_f32_e32 v6, s32, v50
	v_fmac_f32_e32 v7, s33, v50
	v_fmac_f32_e32 v8, s34, v50
	v_fmac_f32_e32 v9, s35, v50
	v_fmac_f32_e32 v10, s36, v50
	v_fmac_f32_e32 v11, s37, v50
	v_fmac_f32_e32 v12, s38, v50
	v_fmac_f32_e32 v13, s39, v50
	v_fmac_f32_e32 v14, s40, v50
	v_fmac_f32_e32 v15, s41, v50
	v_fmac_f32_e32 v16, s42, v50
	v_fmac_f32_e32 v17, s43, v50
	v_fmac_f32_e32 v18, s44, v50
	v_fmac_f32_e32 v19, s45, v50
	v_fmac_f32_e32 v20, s46, v50
	v_fmac_f32_e32 v21, s47, v50
	v_fmac_f32_e32 v22, s48, v50
	s_waitcnt vmcnt(54)
	v_readlane_b32 s32, v24, 9
	v_readlane_b32 s33, v25, 9
	v_readlane_b32 s34, v26, 9
	v_readlane_b32 s35, v27, 9
	v_readlane_b32 s36, v28, 9
	v_readlane_b32 s37, v29, 9
	v_readlane_b32 s38, v30, 9
	v_readlane_b32 s39, v31, 9
	v_readlane_b32 s40, v32, 9
	v_readlane_b32 s41, v33, 9
	v_readlane_b32 s42, v34, 9
	v_readlane_b32 s43, v35, 9
	v_readlane_b32 s44, v36, 9
	v_readlane_b32 s45, v37, 9
	v_readlane_b32 s46, v38, 9
	v_readlane_b32 s47, v39, 9
	v_readlane_b32 s48, v40, 9
	v_fmac_f32_e32 v6, s32, v51
	v_fmac_f32_e32 v7, s33, v51
	v_fmac_f32_e32 v8, s34, v51
	v_fmac_f32_e32 v9, s35, v51
	v_fmac_f32_e32 v10, s36, v51
	v_fmac_f32_e32 v11, s37, v51
	v_fmac_f32_e32 v12, s38, v51
	v_fmac_f32_e32 v13, s39, v51
	v_fmac_f32_e32 v14, s40, v51
	v_fmac_f32_e32 v15, s41, v51
	v_fmac_f32_e32 v16, s42, v51
	v_fmac_f32_e32 v17, s43, v51
	v_fmac_f32_e32 v18, s44, v51
	v_fmac_f32_e32 v19, s45, v51
	v_fmac_f32_e32 v20, s46, v51
	v_fmac_f32_e32 v21, s47, v51
	v_fmac_f32_e32 v22, s48, v51
	s_waitcnt vmcnt(53)
; DI void mods_item(const Params& p, int item, char* smem) {
;     ...
; #pragma unroll 8
;     for (int kk = 0; kk < 64; ++kk) {
;       float wv = W[(size_t)(k0 + kk) * 6144];
; #pragma unroll
;       for (int b = 0; b < 17; ++b) acc[b] += __shfl(s[b], kk, 64) * wv;
;     }
	v_readlane_b32 s32, v24, 10
	v_readlane_b32 s33, v25, 10
	v_readlane_b32 s34, v26, 10
	v_readlane_b32 s35, v27, 10
	v_readlane_b32 s36, v28, 10
	v_readlane_b32 s37, v29, 10
	v_readlane_b32 s38, v30, 10
	v_readlane_b32 s39, v31, 10
	v_readlane_b32 s40, v32, 10
	v_readlane_b32 s41, v33, 10
	v_readlane_b32 s42, v34, 10
	v_readlane_b32 s43, v35, 10
	v_readlane_b32 s44, v36, 10
	v_readlane_b32 s45, v37, 10
	v_readlane_b32 s46, v38, 10
	v_readlane_b32 s47, v39, 10
	v_readlane_b32 s48, v40, 10
	v_fmac_f32_e32 v6, s32, v52
	v_fmac_f32_e32 v7, s33, v52
	v_fmac_f32_e32 v8, s34, v52
	v_fmac_f32_e32 v9, s35, v52
	v_fmac_f32_e32 v10, s36, v52
	v_fmac_f32_e32 v11, s37, v52
	v_fmac_f32_e32 v12, s38, v52
	v_fmac_f32_e32 v13, s39, v52
	v_fmac_f32_e32 v14, s40, v52
	v_fmac_f32_e32 v15, s41, v52
	v_fmac_f32_e32 v16, s42, v52
	v_fmac_f32_e32 v17, s43, v52
	v_fmac_f32_e32 v18, s44, v52
	v_fmac_f32_e32 v19, s45, v52
	v_fmac_f32_e32 v20, s46, v52
	v_fmac_f32_e32 v21, s47, v52
	v_fmac_f32_e32 v22, s48, v52
	s_waitcnt vmcnt(52)
	v_readlane_b32 s32, v24, 11
	v_readlane_b32 s33, v25, 11
	v_readlane_b32 s34, v26, 11
	v_readlane_b32 s35, v27, 11
	v_readlane_b32 s36, v28, 11
	v_readlane_b32 s37, v29, 11
	v_readlane_b32 s38, v30, 11
	v_readlane_b32 s39, v31, 11
	v_readlane_b32 s40, v32, 11
	v_readlane_b32 s41, v33, 11
	v_readlane_b32 s42, v34, 11
	v_readlane_b32 s43, v35, 11
	v_readlane_b32 s44, v36, 11
	v_readlane_b32 s45, v37, 11
	v_readlane_b32 s46, v38, 11
	v_readlane_b32 s47, v39, 11
	v_readlane_b32 s48, v40, 11
	v_fmac_f32_e32 v6, s32, v53
	v_fmac_f32_e32 v7, s33, v53
	v_fmac_f32_e32 v8, s34, v53
	v_fmac_f32_e32 v9, s35, v53
	v_fmac_f32_e32 v10, s36, v53
	v_fmac_f32_e32 v11, s37, v53
	v_fmac_f32_e32 v12, s38, v53
	v_fmac_f32_e32 v13, s39, v53
	v_fmac_f32_e32 v14, s40, v53
	v_fmac_f32_e32 v15, s41, v53
	v_fmac_f32_e32 v16, s42, v53
	v_fmac_f32_e32 v17, s43, v53
	v_fmac_f32_e32 v18, s44, v53
	v_fmac_f32_e32 v19, s45, v53
	v_fmac_f32_e32 v20, s46, v53
	v_fmac_f32_e32 v21, s47, v53
	v_fmac_f32_e32 v22, s48, v53
	s_waitcnt vmcnt(51)
	v_readlane_b32 s32, v24, 12
	v_readlane_b32 s33, v25, 12
	v_readlane_b32 s34, v26, 12
	v_readlane_b32 s35, v27, 12
	v_readlane_b32 s36, v28, 12
	v_readlane_b32 s37, v29, 12
	v_readlane_b32 s38, v30, 12
	v_readlane_b32 s39, v31, 12
	v_readlane_b32 s40, v32, 12
	v_readlane_b32 s41, v33, 12
	v_readlane_b32 s42, v34, 12
	v_readlane_b32 s43, v35, 12
	v_readlane_b32 s44, v36, 12
	v_readlane_b32 s45, v37, 12
	v_readlane_b32 s46, v38, 12
	v_readlane_b32 s47, v39, 12
	v_readlane_b32 s48, v40, 12
	v_fmac_f32_e32 v6, s32, v54
	v_fmac_f32_e32 v7, s33, v54
	v_fmac_f32_e32 v8, s34, v54
	v_fmac_f32_e32 v9, s35, v54
	v_fmac_f32_e32 v10, s36, v54
	v_fmac_f32_e32 v11, s37, v54
	v_fmac_f32_e32 v12, s38, v54
	v_fmac_f32_e32 v13, s39, v54
	v_fmac_f32_e32 v14, s40, v54
	v_fmac_f32_e32 v15, s41, v54
	v_fmac_f32_e32 v16, s42, v54
	v_fmac_f32_e32 v17, s43, v54
	v_fmac_f32_e32 v18, s44, v54
	v_fmac_f32_e32 v19, s45, v54
	v_fmac_f32_e32 v20, s46, v54
	v_fmac_f32_e32 v21, s47, v54
	v_fmac_f32_e32 v22, s48, v54
	s_waitcnt vmcnt(50)
	v_readlane_b32 s32, v24, 13
	v_readlane_b32 s33, v25, 13
	v_readlane_b32 s34, v26, 13
	v_readlane_b32 s35, v27, 13
	v_readlane_b32 s36, v28, 13
	v_readlane_b32 s37, v29, 13
	v_readlane_b32 s38, v30, 13
	v_readlane_b32 s39, v31, 13
	v_readlane_b32 s40, v32, 13
	v_readlane_b32 s41, v33, 13
	v_readlane_b32 s42, v34, 13
	v_readlane_b32 s43, v35, 13
	v_readlane_b32 s44, v36, 13
	v_readlane_b32 s45, v37, 13
	v_readlane_b32 s46, v38, 13
	v_readlane_b32 s47, v39, 13
	v_readlane_b32 s48, v40, 13
	v_fmac_f32_e32 v6, s32, v55
	v_fmac_f32_e32 v7, s33, v55
	v_fmac_f32_e32 v8, s34, v55
	v_fmac_f32_e32 v9, s35, v55
	v_fmac_f32_e32 v10, s36, v55
	v_fmac_f32_e32 v11, s37, v55
	v_fmac_f32_e32 v12, s38, v55
	v_fmac_f32_e32 v13, s39, v55
	v_fmac_f32_e32 v14, s40, v55
	v_fmac_f32_e32 v15, s41, v55
	v_fmac_f32_e32 v16, s42, v55
	v_fmac_f32_e32 v17, s43, v55
	v_fmac_f32_e32 v18, s44, v55
	v_fmac_f32_e32 v19, s45, v55
	v_fmac_f32_e32 v20, s46, v55
	v_fmac_f32_e32 v21, s47, v55
	v_fmac_f32_e32 v22, s48, v55
	s_waitcnt vmcnt(49)
	v_readlane_b32 s32, v24, 14
	v_readlane_b32 s33, v25, 14
	v_readlane_b32 s34, v26, 14
	v_readlane_b32 s35, v27, 14
	v_readlane_b32 s36, v28, 14
	v_readlane_b32 s37, v29, 14
	v_readlane_b32 s38, v30, 14
	v_readlane_b32 s39, v31, 14
	v_readlane_b32 s40, v32, 14
	v_readlane_b32 s41, v33, 14
	v_readlane_b32 s42, v34, 14
	v_readlane_b32 s43, v35, 14
	v_readlane_b32 s44, v36, 14
	v_readlane_b32 s45, v37, 14
	v_readlane_b32 s46, v38, 14
	v_readlane_b32 s47, v39, 14
	v_readlane_b32 s48, v40, 14
	v_fmac_f32_e32 v6, s32, v56
	v_fmac_f32_e32 v7, s33, v56
	v_fmac_f32_e32 v8, s34, v56
	v_fmac_f32_e32 v9, s35, v56
	v_fmac_f32_e32 v10, s36, v56
	v_fmac_f32_e32 v11, s37, v56
	v_fmac_f32_e32 v12, s38, v56
	v_fmac_f32_e32 v13, s39, v56
	v_fmac_f32_e32 v14, s40, v56
	v_fmac_f32_e32 v15, s41, v56
	v_fmac_f32_e32 v16, s42, v56
	v_fmac_f32_e32 v17, s43, v56
	v_fmac_f32_e32 v18, s44, v56
	v_fmac_f32_e32 v19, s45, v56
	v_fmac_f32_e32 v20, s46, v56
	v_fmac_f32_e32 v21, s47, v56
	v_fmac_f32_e32 v22, s48, v56
	s_waitcnt vmcnt(48)
	v_readlane_b32 s32, v24, 15
	v_readlane_b32 s33, v25, 15
	v_readlane_b32 s34, v26, 15
	v_readlane_b32 s35, v27, 15
	v_readlane_b32 s36, v28, 15
	v_readlane_b32 s37, v29, 15
	v_readlane_b32 s38, v30, 15
	v_readlane_b32 s39, v31, 15
	v_readlane_b32 s40, v32, 15
	v_readlane_b32 s41, v33, 15
	v_readlane_b32 s42, v34, 15
	v_readlane_b32 s43, v35, 15
	v_readlane_b32 s44, v36, 15
	v_readlane_b32 s45, v37, 15
	v_readlane_b32 s46, v38, 15
	v_readlane_b32 s47, v39, 15
	v_readlane_b32 s48, v40, 15
	v_fmac_f32_e32 v6, s32, v57
	v_fmac_f32_e32 v7, s33, v57
	v_fmac_f32_e32 v8, s34, v57
	v_fmac_f32_e32 v9, s35, v57
	v_fmac_f32_e32 v10, s36, v57
	v_fmac_f32_e32 v11, s37, v57
	v_fmac_f32_e32 v12, s38, v57
	v_fmac_f32_e32 v13, s39, v57
	v_fmac_f32_e32 v14, s40, v57
	v_fmac_f32_e32 v15, s41, v57
	v_fmac_f32_e32 v16, s42, v57
	v_fmac_f32_e32 v17, s43, v57
	v_fmac_f32_e32 v18, s44, v57
	v_fmac_f32_e32 v19, s45, v57
	v_fmac_f32_e32 v20, s46, v57
	v_fmac_f32_e32 v21, s47, v57
	v_fmac_f32_e32 v22, s48, v57
	s_waitcnt vmcnt(47)
; DI void mods_item(const Params& p, int item, char* smem) {
;     ...
; #pragma unroll 8
;     for (int kk = 0; kk < 64; ++kk) {
;       float wv = W[(size_t)(k0 + kk) * 6144];
; #pragma unroll
;       for (int b = 0; b < 17; ++b) acc[b] += __shfl(s[b], kk, 64) * wv;
;     }
	v_readlane_b32 s32, v24, 16
	v_readlane_b32 s33, v25, 16
	v_readlane_b32 s34, v26, 16
	v_readlane_b32 s35, v27, 16
	v_readlane_b32 s36, v28, 16
	v_readlane_b32 s37, v29, 16
	v_readlane_b32 s38, v30, 16
	v_readlane_b32 s39, v31, 16
	v_readlane_b32 s40, v32, 16
	v_readlane_b32 s41, v33, 16
	v_readlane_b32 s42, v34, 16
	v_readlane_b32 s43, v35, 16
	v_readlane_b32 s44, v36, 16
	v_readlane_b32 s45, v37, 16
	v_readlane_b32 s46, v38, 16
	v_readlane_b32 s47, v39, 16
	v_readlane_b32 s48, v40, 16
	v_fmac_f32_e32 v6, s32, v58
	v_fmac_f32_e32 v7, s33, v58
	v_fmac_f32_e32 v8, s34, v58
	v_fmac_f32_e32 v9, s35, v58
	v_fmac_f32_e32 v10, s36, v58
	v_fmac_f32_e32 v11, s37, v58
	v_fmac_f32_e32 v12, s38, v58
	v_fmac_f32_e32 v13, s39, v58
	v_fmac_f32_e32 v14, s40, v58
	v_fmac_f32_e32 v15, s41, v58
	v_fmac_f32_e32 v16, s42, v58
	v_fmac_f32_e32 v17, s43, v58
	v_fmac_f32_e32 v18, s44, v58
	v_fmac_f32_e32 v19, s45, v58
	v_fmac_f32_e32 v20, s46, v58
	v_fmac_f32_e32 v21, s47, v58
	v_fmac_f32_e32 v22, s48, v58
	s_waitcnt vmcnt(46)
	v_readlane_b32 s32, v24, 17
	v_readlane_b32 s33, v25, 17
	v_readlane_b32 s34, v26, 17
	v_readlane_b32 s35, v27, 17
	v_readlane_b32 s36, v28, 17
	v_readlane_b32 s37, v29, 17
	v_readlane_b32 s38, v30, 17
	v_readlane_b32 s39, v31, 17
	v_readlane_b32 s40, v32, 17
	v_readlane_b32 s41, v33, 17
	v_readlane_b32 s42, v34, 17
	v_readlane_b32 s43, v35, 17
	v_readlane_b32 s44, v36, 17
	v_readlane_b32 s45, v37, 17
	v_readlane_b32 s46, v38, 17
	v_readlane_b32 s47, v39, 17
	v_readlane_b32 s48, v40, 17
	v_fmac_f32_e32 v6, s32, v59
	v_fmac_f32_e32 v7, s33, v59
	v_fmac_f32_e32 v8, s34, v59
	v_fmac_f32_e32 v9, s35, v59
	v_fmac_f32_e32 v10, s36, v59
	v_fmac_f32_e32 v11, s37, v59
	v_fmac_f32_e32 v12, s38, v59
	v_fmac_f32_e32 v13, s39, v59
	v_fmac_f32_e32 v14, s40, v59
	v_fmac_f32_e32 v15, s41, v59
	v_fmac_f32_e32 v16, s42, v59
	v_fmac_f32_e32 v17, s43, v59
	v_fmac_f32_e32 v18, s44, v59
	v_fmac_f32_e32 v19, s45, v59
	v_fmac_f32_e32 v20, s46, v59
	v_fmac_f32_e32 v21, s47, v59
	v_fmac_f32_e32 v22, s48, v59
	s_waitcnt vmcnt(45)
	v_readlane_b32 s32, v24, 18
	v_readlane_b32 s33, v25, 18
	v_readlane_b32 s34, v26, 18
	v_readlane_b32 s35, v27, 18
	v_readlane_b32 s36, v28, 18
	v_readlane_b32 s37, v29, 18
	v_readlane_b32 s38, v30, 18
	v_readlane_b32 s39, v31, 18
	v_readlane_b32 s40, v32, 18
	v_readlane_b32 s41, v33, 18
	v_readlane_b32 s42, v34, 18
	v_readlane_b32 s43, v35, 18
	v_readlane_b32 s44, v36, 18
	v_readlane_b32 s45, v37, 18
	v_readlane_b32 s46, v38, 18
	v_readlane_b32 s47, v39, 18
	v_readlane_b32 s48, v40, 18
	v_fmac_f32_e32 v6, s32, v60
	v_fmac_f32_e32 v7, s33, v60
	v_fmac_f32_e32 v8, s34, v60
	v_fmac_f32_e32 v9, s35, v60
	v_fmac_f32_e32 v10, s36, v60
	v_fmac_f32_e32 v11, s37, v60
	v_fmac_f32_e32 v12, s38, v60
	v_fmac_f32_e32 v13, s39, v60
	v_fmac_f32_e32 v14, s40, v60
	v_fmac_f32_e32 v15, s41, v60
	v_fmac_f32_e32 v16, s42, v60
	v_fmac_f32_e32 v17, s43, v60
	v_fmac_f32_e32 v18, s44, v60
	v_fmac_f32_e32 v19, s45, v60
	v_fmac_f32_e32 v20, s46, v60
	v_fmac_f32_e32 v21, s47, v60
	v_fmac_f32_e32 v22, s48, v60
	s_waitcnt vmcnt(44)
	v_readlane_b32 s32, v24, 19
	v_readlane_b32 s33, v25, 19
	v_readlane_b32 s34, v26, 19
	v_readlane_b32 s35, v27, 19
	v_readlane_b32 s36, v28, 19
	v_readlane_b32 s37, v29, 19
	v_readlane_b32 s38, v30, 19
	v_readlane_b32 s39, v31, 19
	v_readlane_b32 s40, v32, 19
	v_readlane_b32 s41, v33, 19
	v_readlane_b32 s42, v34, 19
	v_readlane_b32 s43, v35, 19
	v_readlane_b32 s44, v36, 19
	v_readlane_b32 s45, v37, 19
	v_readlane_b32 s46, v38, 19
	v_readlane_b32 s47, v39, 19
	v_readlane_b32 s48, v40, 19
	v_fmac_f32_e32 v6, s32, v61
	v_fmac_f32_e32 v7, s33, v61
	v_fmac_f32_e32 v8, s34, v61
	v_fmac_f32_e32 v9, s35, v61
	v_fmac_f32_e32 v10, s36, v61
	v_fmac_f32_e32 v11, s37, v61
	v_fmac_f32_e32 v12, s38, v61
	v_fmac_f32_e32 v13, s39, v61
	v_fmac_f32_e32 v14, s40, v61
	v_fmac_f32_e32 v15, s41, v61
	v_fmac_f32_e32 v16, s42, v61
	v_fmac_f32_e32 v17, s43, v61
	v_fmac_f32_e32 v18, s44, v61
	v_fmac_f32_e32 v19, s45, v61
	v_fmac_f32_e32 v20, s46, v61
	v_fmac_f32_e32 v21, s47, v61
	v_fmac_f32_e32 v22, s48, v61
	s_waitcnt vmcnt(43)
	v_readlane_b32 s32, v24, 20
	v_readlane_b32 s33, v25, 20
	v_readlane_b32 s34, v26, 20
	v_readlane_b32 s35, v27, 20
	v_readlane_b32 s36, v28, 20
	v_readlane_b32 s37, v29, 20
	v_readlane_b32 s38, v30, 20
	v_readlane_b32 s39, v31, 20
	v_readlane_b32 s40, v32, 20
	v_readlane_b32 s41, v33, 20
	v_readlane_b32 s42, v34, 20
	v_readlane_b32 s43, v35, 20
	v_readlane_b32 s44, v36, 20
	v_readlane_b32 s45, v37, 20
	v_readlane_b32 s46, v38, 20
	v_readlane_b32 s47, v39, 20
	v_readlane_b32 s48, v40, 20
	v_fmac_f32_e32 v6, s32, v62
	v_fmac_f32_e32 v7, s33, v62
	v_fmac_f32_e32 v8, s34, v62
	v_fmac_f32_e32 v9, s35, v62
	v_fmac_f32_e32 v10, s36, v62
	v_fmac_f32_e32 v11, s37, v62
	v_fmac_f32_e32 v12, s38, v62
	v_fmac_f32_e32 v13, s39, v62
	v_fmac_f32_e32 v14, s40, v62
	v_fmac_f32_e32 v15, s41, v62
	v_fmac_f32_e32 v16, s42, v62
	v_fmac_f32_e32 v17, s43, v62
	v_fmac_f32_e32 v18, s44, v62
	v_fmac_f32_e32 v19, s45, v62
	v_fmac_f32_e32 v20, s46, v62
	v_fmac_f32_e32 v21, s47, v62
	v_fmac_f32_e32 v22, s48, v62
	s_waitcnt vmcnt(42)
	v_readlane_b32 s32, v24, 21
	v_readlane_b32 s33, v25, 21
	v_readlane_b32 s34, v26, 21
	v_readlane_b32 s35, v27, 21
	v_readlane_b32 s36, v28, 21
	v_readlane_b32 s37, v29, 21
	v_readlane_b32 s38, v30, 21
	v_readlane_b32 s39, v31, 21
	v_readlane_b32 s40, v32, 21
	v_readlane_b32 s41, v33, 21
	v_readlane_b32 s42, v34, 21
	v_readlane_b32 s43, v35, 21
	v_readlane_b32 s44, v36, 21
	v_readlane_b32 s45, v37, 21
	v_readlane_b32 s46, v38, 21
	v_readlane_b32 s47, v39, 21
	v_readlane_b32 s48, v40, 21
	v_fmac_f32_e32 v6, s32, v63
	v_fmac_f32_e32 v7, s33, v63
	v_fmac_f32_e32 v8, s34, v63
	v_fmac_f32_e32 v9, s35, v63
	v_fmac_f32_e32 v10, s36, v63
	v_fmac_f32_e32 v11, s37, v63
	v_fmac_f32_e32 v12, s38, v63
	v_fmac_f32_e32 v13, s39, v63
	v_fmac_f32_e32 v14, s40, v63
	v_fmac_f32_e32 v15, s41, v63
	v_fmac_f32_e32 v16, s42, v63
	v_fmac_f32_e32 v17, s43, v63
	v_fmac_f32_e32 v18, s44, v63
	v_fmac_f32_e32 v19, s45, v63
	v_fmac_f32_e32 v20, s46, v63
	v_fmac_f32_e32 v21, s47, v63
	v_fmac_f32_e32 v22, s48, v63
	s_waitcnt vmcnt(41)
; DI void mods_item(const Params& p, int item, char* smem) {
;     ...
; #pragma unroll 8
;     for (int kk = 0; kk < 64; ++kk) {
;       float wv = W[(size_t)(k0 + kk) * 6144];
; #pragma unroll
;       for (int b = 0; b < 17; ++b) acc[b] += __shfl(s[b], kk, 64) * wv;
;     }
	v_readlane_b32 s32, v24, 22
	v_readlane_b32 s33, v25, 22
	v_readlane_b32 s34, v26, 22
	v_readlane_b32 s35, v27, 22
	v_readlane_b32 s36, v28, 22
	v_readlane_b32 s37, v29, 22
	v_readlane_b32 s38, v30, 22
	v_readlane_b32 s39, v31, 22
	v_readlane_b32 s40, v32, 22
	v_readlane_b32 s41, v33, 22
	v_readlane_b32 s42, v34, 22
	v_readlane_b32 s43, v35, 22
	v_readlane_b32 s44, v36, 22
	v_readlane_b32 s45, v37, 22
	v_readlane_b32 s46, v38, 22
	v_readlane_b32 s47, v39, 22
	v_readlane_b32 s48, v40, 22
	v_fmac_f32_e32 v6, s32, v64
	v_fmac_f32_e32 v7, s33, v64
	v_fmac_f32_e32 v8, s34, v64
	v_fmac_f32_e32 v9, s35, v64
	v_fmac_f32_e32 v10, s36, v64
	v_fmac_f32_e32 v11, s37, v64
	v_fmac_f32_e32 v12, s38, v64
	v_fmac_f32_e32 v13, s39, v64
	v_fmac_f32_e32 v14, s40, v64
	v_fmac_f32_e32 v15, s41, v64
	v_fmac_f32_e32 v16, s42, v64
	v_fmac_f32_e32 v17, s43, v64
	v_fmac_f32_e32 v18, s44, v64
	v_fmac_f32_e32 v19, s45, v64
	v_fmac_f32_e32 v20, s46, v64
	v_fmac_f32_e32 v21, s47, v64
	v_fmac_f32_e32 v22, s48, v64
	s_waitcnt vmcnt(40)
	v_readlane_b32 s32, v24, 23
	v_readlane_b32 s33, v25, 23
	v_readlane_b32 s34, v26, 23
	v_readlane_b32 s35, v27, 23
	v_readlane_b32 s36, v28, 23
	v_readlane_b32 s37, v29, 23
	v_readlane_b32 s38, v30, 23
	v_readlane_b32 s39, v31, 23
	v_readlane_b32 s40, v32, 23
	v_readlane_b32 s41, v33, 23
	v_readlane_b32 s42, v34, 23
	v_readlane_b32 s43, v35, 23
	v_readlane_b32 s44, v36, 23
	v_readlane_b32 s45, v37, 23
	v_readlane_b32 s46, v38, 23
	v_readlane_b32 s47, v39, 23
	v_readlane_b32 s48, v40, 23
	v_fmac_f32_e32 v6, s32, v65
	v_fmac_f32_e32 v7, s33, v65
	v_fmac_f32_e32 v8, s34, v65
	v_fmac_f32_e32 v9, s35, v65
	v_fmac_f32_e32 v10, s36, v65
	v_fmac_f32_e32 v11, s37, v65
	v_fmac_f32_e32 v12, s38, v65
	v_fmac_f32_e32 v13, s39, v65
	v_fmac_f32_e32 v14, s40, v65
	v_fmac_f32_e32 v15, s41, v65
	v_fmac_f32_e32 v16, s42, v65
	v_fmac_f32_e32 v17, s43, v65
	v_fmac_f32_e32 v18, s44, v65
	v_fmac_f32_e32 v19, s45, v65
	v_fmac_f32_e32 v20, s46, v65
	v_fmac_f32_e32 v21, s47, v65
	v_fmac_f32_e32 v22, s48, v65
	s_waitcnt vmcnt(39)
	v_readlane_b32 s32, v24, 24
	v_readlane_b32 s33, v25, 24
	v_readlane_b32 s34, v26, 24
	v_readlane_b32 s35, v27, 24
	v_readlane_b32 s36, v28, 24
	v_readlane_b32 s37, v29, 24
	v_readlane_b32 s38, v30, 24
	v_readlane_b32 s39, v31, 24
	v_readlane_b32 s40, v32, 24
	v_readlane_b32 s41, v33, 24
	v_readlane_b32 s42, v34, 24
	v_readlane_b32 s43, v35, 24
	v_readlane_b32 s44, v36, 24
	v_readlane_b32 s45, v37, 24
	v_readlane_b32 s46, v38, 24
	v_readlane_b32 s47, v39, 24
	v_readlane_b32 s48, v40, 24
	v_fmac_f32_e32 v6, s32, v66
	v_fmac_f32_e32 v7, s33, v66
	v_fmac_f32_e32 v8, s34, v66
	v_fmac_f32_e32 v9, s35, v66
	v_fmac_f32_e32 v10, s36, v66
	v_fmac_f32_e32 v11, s37, v66
	v_fmac_f32_e32 v12, s38, v66
	v_fmac_f32_e32 v13, s39, v66
	v_fmac_f32_e32 v14, s40, v66
	v_fmac_f32_e32 v15, s41, v66
	v_fmac_f32_e32 v16, s42, v66
	v_fmac_f32_e32 v17, s43, v66
	v_fmac_f32_e32 v18, s44, v66
	v_fmac_f32_e32 v19, s45, v66
	v_fmac_f32_e32 v20, s46, v66
	v_fmac_f32_e32 v21, s47, v66
	v_fmac_f32_e32 v22, s48, v66
	s_waitcnt vmcnt(38)
	v_readlane_b32 s32, v24, 25
	v_readlane_b32 s33, v25, 25
	v_readlane_b32 s34, v26, 25
	v_readlane_b32 s35, v27, 25
	v_readlane_b32 s36, v28, 25
	v_readlane_b32 s37, v29, 25
	v_readlane_b32 s38, v30, 25
	v_readlane_b32 s39, v31, 25
	v_readlane_b32 s40, v32, 25
	v_readlane_b32 s41, v33, 25
	v_readlane_b32 s42, v34, 25
	v_readlane_b32 s43, v35, 25
	v_readlane_b32 s44, v36, 25
	v_readlane_b32 s45, v37, 25
	v_readlane_b32 s46, v38, 25
	v_readlane_b32 s47, v39, 25
	v_readlane_b32 s48, v40, 25
	v_fmac_f32_e32 v6, s32, v67
	v_fmac_f32_e32 v7, s33, v67
	v_fmac_f32_e32 v8, s34, v67
	v_fmac_f32_e32 v9, s35, v67
	v_fmac_f32_e32 v10, s36, v67
	v_fmac_f32_e32 v11, s37, v67
	v_fmac_f32_e32 v12, s38, v67
	v_fmac_f32_e32 v13, s39, v67
	v_fmac_f32_e32 v14, s40, v67
	v_fmac_f32_e32 v15, s41, v67
	v_fmac_f32_e32 v16, s42, v67
	v_fmac_f32_e32 v17, s43, v67
	v_fmac_f32_e32 v18, s44, v67
	v_fmac_f32_e32 v19, s45, v67
	v_fmac_f32_e32 v20, s46, v67
	v_fmac_f32_e32 v21, s47, v67
	v_fmac_f32_e32 v22, s48, v67
	s_waitcnt vmcnt(37)
	v_readlane_b32 s32, v24, 26
	v_readlane_b32 s33, v25, 26
	v_readlane_b32 s34, v26, 26
	v_readlane_b32 s35, v27, 26
	v_readlane_b32 s36, v28, 26
	v_readlane_b32 s37, v29, 26
	v_readlane_b32 s38, v30, 26
	v_readlane_b32 s39, v31, 26
	v_readlane_b32 s40, v32, 26
	v_readlane_b32 s41, v33, 26
	v_readlane_b32 s42, v34, 26
	v_readlane_b32 s43, v35, 26
	v_readlane_b32 s44, v36, 26
	v_readlane_b32 s45, v37, 26
	v_readlane_b32 s46, v38, 26
	v_readlane_b32 s47, v39, 26
	v_readlane_b32 s48, v40, 26
	v_fmac_f32_e32 v6, s32, v68
	v_fmac_f32_e32 v7, s33, v68
	v_fmac_f32_e32 v8, s34, v68
	v_fmac_f32_e32 v9, s35, v68
	v_fmac_f32_e32 v10, s36, v68
	v_fmac_f32_e32 v11, s37, v68
	v_fmac_f32_e32 v12, s38, v68
	v_fmac_f32_e32 v13, s39, v68
	v_fmac_f32_e32 v14, s40, v68
	v_fmac_f32_e32 v15, s41, v68
	v_fmac_f32_e32 v16, s42, v68
	v_fmac_f32_e32 v17, s43, v68
	v_fmac_f32_e32 v18, s44, v68
	v_fmac_f32_e32 v19, s45, v68
	v_fmac_f32_e32 v20, s46, v68
	v_fmac_f32_e32 v21, s47, v68
	v_fmac_f32_e32 v22, s48, v68
	s_waitcnt vmcnt(36)
	v_readlane_b32 s32, v24, 27
	v_readlane_b32 s33, v25, 27
	v_readlane_b32 s34, v26, 27
	v_readlane_b32 s35, v27, 27
	v_readlane_b32 s36, v28, 27
	v_readlane_b32 s37, v29, 27
	v_readlane_b32 s38, v30, 27
	v_readlane_b32 s39, v31, 27
	v_readlane_b32 s40, v32, 27
	v_readlane_b32 s41, v33, 27
	v_readlane_b32 s42, v34, 27
	v_readlane_b32 s43, v35, 27
	v_readlane_b32 s44, v36, 27
	v_readlane_b32 s45, v37, 27
	v_readlane_b32 s46, v38, 27
	v_readlane_b32 s47, v39, 27
	v_readlane_b32 s48, v40, 27
	v_fmac_f32_e32 v6, s32, v69
	v_fmac_f32_e32 v7, s33, v69
	v_fmac_f32_e32 v8, s34, v69
	v_fmac_f32_e32 v9, s35, v69
	v_fmac_f32_e32 v10, s36, v69
	v_fmac_f32_e32 v11, s37, v69
	v_fmac_f32_e32 v12, s38, v69
	v_fmac_f32_e32 v13, s39, v69
	v_fmac_f32_e32 v14, s40, v69
	v_fmac_f32_e32 v15, s41, v69
	v_fmac_f32_e32 v16, s42, v69
	v_fmac_f32_e32 v17, s43, v69
	v_fmac_f32_e32 v18, s44, v69
	v_fmac_f32_e32 v19, s45, v69
	v_fmac_f32_e32 v20, s46, v69
	v_fmac_f32_e32 v21, s47, v69
	v_fmac_f32_e32 v22, s48, v69
	s_waitcnt vmcnt(35)
; DI void mods_item(const Params& p, int item, char* smem) {
;     ...
; #pragma unroll 8
;     for (int kk = 0; kk < 64; ++kk) {
;       float wv = W[(size_t)(k0 + kk) * 6144];
; #pragma unroll
;       for (int b = 0; b < 17; ++b) acc[b] += __shfl(s[b], kk, 64) * wv;
;     }
	v_readlane_b32 s32, v24, 28
	v_readlane_b32 s33, v25, 28
	v_readlane_b32 s34, v26, 28
	v_readlane_b32 s35, v27, 28
	v_readlane_b32 s36, v28, 28
	v_readlane_b32 s37, v29, 28
	v_readlane_b32 s38, v30, 28
	v_readlane_b32 s39, v31, 28
	v_readlane_b32 s40, v32, 28
	v_readlane_b32 s41, v33, 28
	v_readlane_b32 s42, v34, 28
	v_readlane_b32 s43, v35, 28
	v_readlane_b32 s44, v36, 28
	v_readlane_b32 s45, v37, 28
	v_readlane_b32 s46, v38, 28
	v_readlane_b32 s47, v39, 28
	v_readlane_b32 s48, v40, 28
	v_fmac_f32_e32 v6, s32, v70
	v_fmac_f32_e32 v7, s33, v70
	v_fmac_f32_e32 v8, s34, v70
	v_fmac_f32_e32 v9, s35, v70
	v_fmac_f32_e32 v10, s36, v70
	v_fmac_f32_e32 v11, s37, v70
	v_fmac_f32_e32 v12, s38, v70
	v_fmac_f32_e32 v13, s39, v70
	v_fmac_f32_e32 v14, s40, v70
	v_fmac_f32_e32 v15, s41, v70
	v_fmac_f32_e32 v16, s42, v70
	v_fmac_f32_e32 v17, s43, v70
	v_fmac_f32_e32 v18, s44, v70
	v_fmac_f32_e32 v19, s45, v70
	v_fmac_f32_e32 v20, s46, v70
	v_fmac_f32_e32 v21, s47, v70
	v_fmac_f32_e32 v22, s48, v70
	s_waitcnt vmcnt(34)
	v_readlane_b32 s32, v24, 29
	v_readlane_b32 s33, v25, 29
	v_readlane_b32 s34, v26, 29
	v_readlane_b32 s35, v27, 29
	v_readlane_b32 s36, v28, 29
	v_readlane_b32 s37, v29, 29
	v_readlane_b32 s38, v30, 29
	v_readlane_b32 s39, v31, 29
	v_readlane_b32 s40, v32, 29
	v_readlane_b32 s41, v33, 29
	v_readlane_b32 s42, v34, 29
	v_readlane_b32 s43, v35, 29
	v_readlane_b32 s44, v36, 29
	v_readlane_b32 s45, v37, 29
	v_readlane_b32 s46, v38, 29
	v_readlane_b32 s47, v39, 29
	v_readlane_b32 s48, v40, 29
	v_fmac_f32_e32 v6, s32, v71
	v_fmac_f32_e32 v7, s33, v71
	v_fmac_f32_e32 v8, s34, v71
	v_fmac_f32_e32 v9, s35, v71
	v_fmac_f32_e32 v10, s36, v71
	v_fmac_f32_e32 v11, s37, v71
	v_fmac_f32_e32 v12, s38, v71
	v_fmac_f32_e32 v13, s39, v71
	v_fmac_f32_e32 v14, s40, v71
	v_fmac_f32_e32 v15, s41, v71
	v_fmac_f32_e32 v16, s42, v71
	v_fmac_f32_e32 v17, s43, v71
	v_fmac_f32_e32 v18, s44, v71
	v_fmac_f32_e32 v19, s45, v71
	v_fmac_f32_e32 v20, s46, v71
	v_fmac_f32_e32 v21, s47, v71
	v_fmac_f32_e32 v22, s48, v71
	s_waitcnt vmcnt(33)
	v_readlane_b32 s32, v24, 30
	v_readlane_b32 s33, v25, 30
	v_readlane_b32 s34, v26, 30
	v_readlane_b32 s35, v27, 30
	v_readlane_b32 s36, v28, 30
	v_readlane_b32 s37, v29, 30
	v_readlane_b32 s38, v30, 30
	v_readlane_b32 s39, v31, 30
	v_readlane_b32 s40, v32, 30
	v_readlane_b32 s41, v33, 30
	v_readlane_b32 s42, v34, 30
	v_readlane_b32 s43, v35, 30
	v_readlane_b32 s44, v36, 30
	v_readlane_b32 s45, v37, 30
	v_readlane_b32 s46, v38, 30
	v_readlane_b32 s47, v39, 30
	v_readlane_b32 s48, v40, 30
	v_fmac_f32_e32 v6, s32, v72
	v_fmac_f32_e32 v7, s33, v72
	v_fmac_f32_e32 v8, s34, v72
	v_fmac_f32_e32 v9, s35, v72
	v_fmac_f32_e32 v10, s36, v72
	v_fmac_f32_e32 v11, s37, v72
	v_fmac_f32_e32 v12, s38, v72
	v_fmac_f32_e32 v13, s39, v72
	v_fmac_f32_e32 v14, s40, v72
	v_fmac_f32_e32 v15, s41, v72
	v_fmac_f32_e32 v16, s42, v72
	v_fmac_f32_e32 v17, s43, v72
	v_fmac_f32_e32 v18, s44, v72
	v_fmac_f32_e32 v19, s45, v72
	v_fmac_f32_e32 v20, s46, v72
	v_fmac_f32_e32 v21, s47, v72
	v_fmac_f32_e32 v22, s48, v72
	s_waitcnt vmcnt(32)
	v_readlane_b32 s32, v24, 31
	v_readlane_b32 s33, v25, 31
	v_readlane_b32 s34, v26, 31
	v_readlane_b32 s35, v27, 31
	v_readlane_b32 s36, v28, 31
	v_readlane_b32 s37, v29, 31
	v_readlane_b32 s38, v30, 31
	v_readlane_b32 s39, v31, 31
	v_readlane_b32 s40, v32, 31
	v_readlane_b32 s41, v33, 31
	v_readlane_b32 s42, v34, 31
	v_readlane_b32 s43, v35, 31
	v_readlane_b32 s44, v36, 31
	v_readlane_b32 s45, v37, 31
	v_readlane_b32 s46, v38, 31
	v_readlane_b32 s47, v39, 31
	v_readlane_b32 s48, v40, 31
	v_fmac_f32_e32 v6, s32, v73
	v_fmac_f32_e32 v7, s33, v73
	v_fmac_f32_e32 v8, s34, v73
	v_fmac_f32_e32 v9, s35, v73
	v_fmac_f32_e32 v10, s36, v73
	v_fmac_f32_e32 v11, s37, v73
	v_fmac_f32_e32 v12, s38, v73
	v_fmac_f32_e32 v13, s39, v73
	v_fmac_f32_e32 v14, s40, v73
	v_fmac_f32_e32 v15, s41, v73
	v_fmac_f32_e32 v16, s42, v73
	v_fmac_f32_e32 v17, s43, v73
	v_fmac_f32_e32 v18, s44, v73
	v_fmac_f32_e32 v19, s45, v73
	v_fmac_f32_e32 v20, s46, v73
	v_fmac_f32_e32 v21, s47, v73
	v_fmac_f32_e32 v22, s48, v73
	s_waitcnt vmcnt(31)
	v_readlane_b32 s32, v24, 32
	v_readlane_b32 s33, v25, 32
	v_readlane_b32 s34, v26, 32
	v_readlane_b32 s35, v27, 32
	v_readlane_b32 s36, v28, 32
	v_readlane_b32 s37, v29, 32
	v_readlane_b32 s38, v30, 32
	v_readlane_b32 s39, v31, 32
	v_readlane_b32 s40, v32, 32
	v_readlane_b32 s41, v33, 32
	v_readlane_b32 s42, v34, 32
	v_readlane_b32 s43, v35, 32
	v_readlane_b32 s44, v36, 32
	v_readlane_b32 s45, v37, 32
	v_readlane_b32 s46, v38, 32
	v_readlane_b32 s47, v39, 32
	v_readlane_b32 s48, v40, 32
	v_fmac_f32_e32 v6, s32, v74
	v_fmac_f32_e32 v7, s33, v74
	v_fmac_f32_e32 v8, s34, v74
	v_fmac_f32_e32 v9, s35, v74
	v_fmac_f32_e32 v10, s36, v74
	v_fmac_f32_e32 v11, s37, v74
	v_fmac_f32_e32 v12, s38, v74
	v_fmac_f32_e32 v13, s39, v74
	v_fmac_f32_e32 v14, s40, v74
	v_fmac_f32_e32 v15, s41, v74
	v_fmac_f32_e32 v16, s42, v74
	v_fmac_f32_e32 v17, s43, v74
	v_fmac_f32_e32 v18, s44, v74
	v_fmac_f32_e32 v19, s45, v74
	v_fmac_f32_e32 v20, s46, v74
	v_fmac_f32_e32 v21, s47, v74
	v_fmac_f32_e32 v22, s48, v74
	s_waitcnt vmcnt(30)
	v_readlane_b32 s32, v24, 33
	v_readlane_b32 s33, v25, 33
	v_readlane_b32 s34, v26, 33
	v_readlane_b32 s35, v27, 33
	v_readlane_b32 s36, v28, 33
	v_readlane_b32 s37, v29, 33
	v_readlane_b32 s38, v30, 33
	v_readlane_b32 s39, v31, 33
	v_readlane_b32 s40, v32, 33
	v_readlane_b32 s41, v33, 33
	v_readlane_b32 s42, v34, 33
	v_readlane_b32 s43, v35, 33
	v_readlane_b32 s44, v36, 33
	v_readlane_b32 s45, v37, 33
	v_readlane_b32 s46, v38, 33
	v_readlane_b32 s47, v39, 33
	v_readlane_b32 s48, v40, 33
	v_fmac_f32_e32 v6, s32, v75
	v_fmac_f32_e32 v7, s33, v75
	v_fmac_f32_e32 v8, s34, v75
	v_fmac_f32_e32 v9, s35, v75
	v_fmac_f32_e32 v10, s36, v75
	v_fmac_f32_e32 v11, s37, v75
	v_fmac_f32_e32 v12, s38, v75
	v_fmac_f32_e32 v13, s39, v75
	v_fmac_f32_e32 v14, s40, v75
	v_fmac_f32_e32 v15, s41, v75
	v_fmac_f32_e32 v16, s42, v75
	v_fmac_f32_e32 v17, s43, v75
	v_fmac_f32_e32 v18, s44, v75
	v_fmac_f32_e32 v19, s45, v75
	v_fmac_f32_e32 v20, s46, v75
	v_fmac_f32_e32 v21, s47, v75
	v_fmac_f32_e32 v22, s48, v75
	s_waitcnt vmcnt(29)
; DI void mods_item(const Params& p, int item, char* smem) {
;     ...
; #pragma unroll 8
;     for (int kk = 0; kk < 64; ++kk) {
;       float wv = W[(size_t)(k0 + kk) * 6144];
; #pragma unroll
;       for (int b = 0; b < 17; ++b) acc[b] += __shfl(s[b], kk, 64) * wv;
;     }
	v_readlane_b32 s32, v24, 34
	v_readlane_b32 s33, v25, 34
	v_readlane_b32 s34, v26, 34
	v_readlane_b32 s35, v27, 34
	v_readlane_b32 s36, v28, 34
	v_readlane_b32 s37, v29, 34
	v_readlane_b32 s38, v30, 34
	v_readlane_b32 s39, v31, 34
	v_readlane_b32 s40, v32, 34
	v_readlane_b32 s41, v33, 34
	v_readlane_b32 s42, v34, 34
	v_readlane_b32 s43, v35, 34
	v_readlane_b32 s44, v36, 34
	v_readlane_b32 s45, v37, 34
	v_readlane_b32 s46, v38, 34
	v_readlane_b32 s47, v39, 34
	v_readlane_b32 s48, v40, 34
	v_fmac_f32_e32 v6, s32, v76
	v_fmac_f32_e32 v7, s33, v76
	v_fmac_f32_e32 v8, s34, v76
	v_fmac_f32_e32 v9, s35, v76
	v_fmac_f32_e32 v10, s36, v76
	v_fmac_f32_e32 v11, s37, v76
	v_fmac_f32_e32 v12, s38, v76
	v_fmac_f32_e32 v13, s39, v76
	v_fmac_f32_e32 v14, s40, v76
	v_fmac_f32_e32 v15, s41, v76
	v_fmac_f32_e32 v16, s42, v76
	v_fmac_f32_e32 v17, s43, v76
	v_fmac_f32_e32 v18, s44, v76
	v_fmac_f32_e32 v19, s45, v76
	v_fmac_f32_e32 v20, s46, v76
	v_fmac_f32_e32 v21, s47, v76
	v_fmac_f32_e32 v22, s48, v76
	s_waitcnt vmcnt(28)
	v_readlane_b32 s32, v24, 35
	v_readlane_b32 s33, v25, 35
	v_readlane_b32 s34, v26, 35
	v_readlane_b32 s35, v27, 35
	v_readlane_b32 s36, v28, 35
	v_readlane_b32 s37, v29, 35
	v_readlane_b32 s38, v30, 35
	v_readlane_b32 s39, v31, 35
	v_readlane_b32 s40, v32, 35
	v_readlane_b32 s41, v33, 35
	v_readlane_b32 s42, v34, 35
	v_readlane_b32 s43, v35, 35
	v_readlane_b32 s44, v36, 35
	v_readlane_b32 s45, v37, 35
	v_readlane_b32 s46, v38, 35
	v_readlane_b32 s47, v39, 35
	v_readlane_b32 s48, v40, 35
	v_fmac_f32_e32 v6, s32, v77
	v_fmac_f32_e32 v7, s33, v77
	v_fmac_f32_e32 v8, s34, v77
	v_fmac_f32_e32 v9, s35, v77
	v_fmac_f32_e32 v10, s36, v77
	v_fmac_f32_e32 v11, s37, v77
	v_fmac_f32_e32 v12, s38, v77
	v_fmac_f32_e32 v13, s39, v77
	v_fmac_f32_e32 v14, s40, v77
	v_fmac_f32_e32 v15, s41, v77
	v_fmac_f32_e32 v16, s42, v77
	v_fmac_f32_e32 v17, s43, v77
	v_fmac_f32_e32 v18, s44, v77
	v_fmac_f32_e32 v19, s45, v77
	v_fmac_f32_e32 v20, s46, v77
	v_fmac_f32_e32 v21, s47, v77
	v_fmac_f32_e32 v22, s48, v77
	s_waitcnt vmcnt(27)
	v_readlane_b32 s32, v24, 36
	v_readlane_b32 s33, v25, 36
	v_readlane_b32 s34, v26, 36
	v_readlane_b32 s35, v27, 36
	v_readlane_b32 s36, v28, 36
	v_readlane_b32 s37, v29, 36
	v_readlane_b32 s38, v30, 36
	v_readlane_b32 s39, v31, 36
	v_readlane_b32 s40, v32, 36
	v_readlane_b32 s41, v33, 36
	v_readlane_b32 s42, v34, 36
	v_readlane_b32 s43, v35, 36
	v_readlane_b32 s44, v36, 36
	v_readlane_b32 s45, v37, 36
	v_readlane_b32 s46, v38, 36
	v_readlane_b32 s47, v39, 36
	v_readlane_b32 s48, v40, 36
	v_fmac_f32_e32 v6, s32, v78
	v_fmac_f32_e32 v7, s33, v78
	v_fmac_f32_e32 v8, s34, v78
	v_fmac_f32_e32 v9, s35, v78
	v_fmac_f32_e32 v10, s36, v78
	v_fmac_f32_e32 v11, s37, v78
	v_fmac_f32_e32 v12, s38, v78
	v_fmac_f32_e32 v13, s39, v78
	v_fmac_f32_e32 v14, s40, v78
	v_fmac_f32_e32 v15, s41, v78
	v_fmac_f32_e32 v16, s42, v78
	v_fmac_f32_e32 v17, s43, v78
	v_fmac_f32_e32 v18, s44, v78
	v_fmac_f32_e32 v19, s45, v78
	v_fmac_f32_e32 v20, s46, v78
	v_fmac_f32_e32 v21, s47, v78
	v_fmac_f32_e32 v22, s48, v78
	s_waitcnt vmcnt(26)
	v_readlane_b32 s32, v24, 37
	v_readlane_b32 s33, v25, 37
	v_readlane_b32 s34, v26, 37
	v_readlane_b32 s35, v27, 37
	v_readlane_b32 s36, v28, 37
	v_readlane_b32 s37, v29, 37
	v_readlane_b32 s38, v30, 37
	v_readlane_b32 s39, v31, 37
	v_readlane_b32 s40, v32, 37
	v_readlane_b32 s41, v33, 37
	v_readlane_b32 s42, v34, 37
	v_readlane_b32 s43, v35, 37
	v_readlane_b32 s44, v36, 37
	v_readlane_b32 s45, v37, 37
	v_readlane_b32 s46, v38, 37
	v_readlane_b32 s47, v39, 37
	v_readlane_b32 s48, v40, 37
	v_fmac_f32_e32 v6, s32, v79
	v_fmac_f32_e32 v7, s33, v79
	v_fmac_f32_e32 v8, s34, v79
	v_fmac_f32_e32 v9, s35, v79
	v_fmac_f32_e32 v10, s36, v79
	v_fmac_f32_e32 v11, s37, v79
	v_fmac_f32_e32 v12, s38, v79
	v_fmac_f32_e32 v13, s39, v79
	v_fmac_f32_e32 v14, s40, v79
	v_fmac_f32_e32 v15, s41, v79
	v_fmac_f32_e32 v16, s42, v79
	v_fmac_f32_e32 v17, s43, v79
	v_fmac_f32_e32 v18, s44, v79
	v_fmac_f32_e32 v19, s45, v79
	v_fmac_f32_e32 v20, s46, v79
	v_fmac_f32_e32 v21, s47, v79
	v_fmac_f32_e32 v22, s48, v79
	s_waitcnt vmcnt(25)
	v_readlane_b32 s32, v24, 38
	v_readlane_b32 s33, v25, 38
	v_readlane_b32 s34, v26, 38
	v_readlane_b32 s35, v27, 38
	v_readlane_b32 s36, v28, 38
	v_readlane_b32 s37, v29, 38
	v_readlane_b32 s38, v30, 38
	v_readlane_b32 s39, v31, 38
	v_readlane_b32 s40, v32, 38
	v_readlane_b32 s41, v33, 38
	v_readlane_b32 s42, v34, 38
	v_readlane_b32 s43, v35, 38
	v_readlane_b32 s44, v36, 38
	v_readlane_b32 s45, v37, 38
	v_readlane_b32 s46, v38, 38
	v_readlane_b32 s47, v39, 38
	v_readlane_b32 s48, v40, 38
	v_fmac_f32_e32 v6, s32, v80
	v_fmac_f32_e32 v7, s33, v80
	v_fmac_f32_e32 v8, s34, v80
	v_fmac_f32_e32 v9, s35, v80
	v_fmac_f32_e32 v10, s36, v80
	v_fmac_f32_e32 v11, s37, v80
	v_fmac_f32_e32 v12, s38, v80
	v_fmac_f32_e32 v13, s39, v80
	v_fmac_f32_e32 v14, s40, v80
	v_fmac_f32_e32 v15, s41, v80
	v_fmac_f32_e32 v16, s42, v80
	v_fmac_f32_e32 v17, s43, v80
	v_fmac_f32_e32 v18, s44, v80
	v_fmac_f32_e32 v19, s45, v80
	v_fmac_f32_e32 v20, s46, v80
	v_fmac_f32_e32 v21, s47, v80
	v_fmac_f32_e32 v22, s48, v80
	s_waitcnt vmcnt(24)
	v_readlane_b32 s32, v24, 39
	v_readlane_b32 s33, v25, 39
	v_readlane_b32 s34, v26, 39
	v_readlane_b32 s35, v27, 39
	v_readlane_b32 s36, v28, 39
	v_readlane_b32 s37, v29, 39
	v_readlane_b32 s38, v30, 39
	v_readlane_b32 s39, v31, 39
	v_readlane_b32 s40, v32, 39
	v_readlane_b32 s41, v33, 39
	v_readlane_b32 s42, v34, 39
	v_readlane_b32 s43, v35, 39
	v_readlane_b32 s44, v36, 39
	v_readlane_b32 s45, v37, 39
	v_readlane_b32 s46, v38, 39
	v_readlane_b32 s47, v39, 39
	v_readlane_b32 s48, v40, 39
	v_fmac_f32_e32 v6, s32, v81
	v_fmac_f32_e32 v7, s33, v81
	v_fmac_f32_e32 v8, s34, v81
	v_fmac_f32_e32 v9, s35, v81
	v_fmac_f32_e32 v10, s36, v81
	v_fmac_f32_e32 v11, s37, v81
	v_fmac_f32_e32 v12, s38, v81
	v_fmac_f32_e32 v13, s39, v81
	v_fmac_f32_e32 v14, s40, v81
	v_fmac_f32_e32 v15, s41, v81
	v_fmac_f32_e32 v16, s42, v81
	v_fmac_f32_e32 v17, s43, v81
	v_fmac_f32_e32 v18, s44, v81
	v_fmac_f32_e32 v19, s45, v81
	v_fmac_f32_e32 v20, s46, v81
	v_fmac_f32_e32 v21, s47, v81
	v_fmac_f32_e32 v22, s48, v81
	s_waitcnt vmcnt(23)
; DI void mods_item(const Params& p, int item, char* smem) {
;     ...
; #pragma unroll 8
;     for (int kk = 0; kk < 64; ++kk) {
;       float wv = W[(size_t)(k0 + kk) * 6144];
; #pragma unroll
;       for (int b = 0; b < 17; ++b) acc[b] += __shfl(s[b], kk, 64) * wv;
;     }
	v_readlane_b32 s32, v24, 40
	v_readlane_b32 s33, v25, 40
	v_readlane_b32 s34, v26, 40
	v_readlane_b32 s35, v27, 40
	v_readlane_b32 s36, v28, 40
	v_readlane_b32 s37, v29, 40
	v_readlane_b32 s38, v30, 40
	v_readlane_b32 s39, v31, 40
	v_readlane_b32 s40, v32, 40
	v_readlane_b32 s41, v33, 40
	v_readlane_b32 s42, v34, 40
	v_readlane_b32 s43, v35, 40
	v_readlane_b32 s44, v36, 40
	v_readlane_b32 s45, v37, 40
	v_readlane_b32 s46, v38, 40
	v_readlane_b32 s47, v39, 40
	v_readlane_b32 s48, v40, 40
	v_fmac_f32_e32 v6, s32, v82
	v_fmac_f32_e32 v7, s33, v82
	v_fmac_f32_e32 v8, s34, v82
	v_fmac_f32_e32 v9, s35, v82
	v_fmac_f32_e32 v10, s36, v82
	v_fmac_f32_e32 v11, s37, v82
	v_fmac_f32_e32 v12, s38, v82
	v_fmac_f32_e32 v13, s39, v82
	v_fmac_f32_e32 v14, s40, v82
	v_fmac_f32_e32 v15, s41, v82
	v_fmac_f32_e32 v16, s42, v82
	v_fmac_f32_e32 v17, s43, v82
	v_fmac_f32_e32 v18, s44, v82
	v_fmac_f32_e32 v19, s45, v82
	v_fmac_f32_e32 v20, s46, v82
	v_fmac_f32_e32 v21, s47, v82
	v_fmac_f32_e32 v22, s48, v82
	s_waitcnt vmcnt(22)
	v_readlane_b32 s32, v24, 41
	v_readlane_b32 s33, v25, 41
	v_readlane_b32 s34, v26, 41
	v_readlane_b32 s35, v27, 41
	v_readlane_b32 s36, v28, 41
	v_readlane_b32 s37, v29, 41
	v_readlane_b32 s38, v30, 41
	v_readlane_b32 s39, v31, 41
	v_readlane_b32 s40, v32, 41
	v_readlane_b32 s41, v33, 41
	v_readlane_b32 s42, v34, 41
	v_readlane_b32 s43, v35, 41
	v_readlane_b32 s44, v36, 41
	v_readlane_b32 s45, v37, 41
	v_readlane_b32 s46, v38, 41
	v_readlane_b32 s47, v39, 41
	v_readlane_b32 s48, v40, 41
	v_fmac_f32_e32 v6, s32, v83
	v_fmac_f32_e32 v7, s33, v83
	v_fmac_f32_e32 v8, s34, v83
	v_fmac_f32_e32 v9, s35, v83
	v_fmac_f32_e32 v10, s36, v83
	v_fmac_f32_e32 v11, s37, v83
	v_fmac_f32_e32 v12, s38, v83
	v_fmac_f32_e32 v13, s39, v83
	v_fmac_f32_e32 v14, s40, v83
	v_fmac_f32_e32 v15, s41, v83
	v_fmac_f32_e32 v16, s42, v83
	v_fmac_f32_e32 v17, s43, v83
	v_fmac_f32_e32 v18, s44, v83
	v_fmac_f32_e32 v19, s45, v83
	v_fmac_f32_e32 v20, s46, v83
	v_fmac_f32_e32 v21, s47, v83
	v_fmac_f32_e32 v22, s48, v83
	s_waitcnt vmcnt(21)
	v_readlane_b32 s32, v24, 42
	v_readlane_b32 s33, v25, 42
	v_readlane_b32 s34, v26, 42
	v_readlane_b32 s35, v27, 42
	v_readlane_b32 s36, v28, 42
	v_readlane_b32 s37, v29, 42
	v_readlane_b32 s38, v30, 42
	v_readlane_b32 s39, v31, 42
	v_readlane_b32 s40, v32, 42
	v_readlane_b32 s41, v33, 42
	v_readlane_b32 s42, v34, 42
	v_readlane_b32 s43, v35, 42
	v_readlane_b32 s44, v36, 42
	v_readlane_b32 s45, v37, 42
	v_readlane_b32 s46, v38, 42
	v_readlane_b32 s47, v39, 42
	v_readlane_b32 s48, v40, 42
	v_fmac_f32_e32 v6, s32, v84
	v_fmac_f32_e32 v7, s33, v84
	v_fmac_f32_e32 v8, s34, v84
	v_fmac_f32_e32 v9, s35, v84
	v_fmac_f32_e32 v10, s36, v84
	v_fmac_f32_e32 v11, s37, v84
	v_fmac_f32_e32 v12, s38, v84
	v_fmac_f32_e32 v13, s39, v84
	v_fmac_f32_e32 v14, s40, v84
	v_fmac_f32_e32 v15, s41, v84
	v_fmac_f32_e32 v16, s42, v84
	v_fmac_f32_e32 v17, s43, v84
	v_fmac_f32_e32 v18, s44, v84
	v_fmac_f32_e32 v19, s45, v84
	v_fmac_f32_e32 v20, s46, v84
	v_fmac_f32_e32 v21, s47, v84
	v_fmac_f32_e32 v22, s48, v84
	s_waitcnt vmcnt(20)
	v_readlane_b32 s32, v24, 43
	v_readlane_b32 s33, v25, 43
	v_readlane_b32 s34, v26, 43
	v_readlane_b32 s35, v27, 43
	v_readlane_b32 s36, v28, 43
	v_readlane_b32 s37, v29, 43
	v_readlane_b32 s38, v30, 43
	v_readlane_b32 s39, v31, 43
	v_readlane_b32 s40, v32, 43
	v_readlane_b32 s41, v33, 43
	v_readlane_b32 s42, v34, 43
	v_readlane_b32 s43, v35, 43
	v_readlane_b32 s44, v36, 43
	v_readlane_b32 s45, v37, 43
	v_readlane_b32 s46, v38, 43
	v_readlane_b32 s47, v39, 43
	v_readlane_b32 s48, v40, 43
	v_fmac_f32_e32 v6, s32, v85
	v_fmac_f32_e32 v7, s33, v85
	v_fmac_f32_e32 v8, s34, v85
	v_fmac_f32_e32 v9, s35, v85
	v_fmac_f32_e32 v10, s36, v85
	v_fmac_f32_e32 v11, s37, v85
	v_fmac_f32_e32 v12, s38, v85
	v_fmac_f32_e32 v13, s39, v85
	v_fmac_f32_e32 v14, s40, v85
	v_fmac_f32_e32 v15, s41, v85
	v_fmac_f32_e32 v16, s42, v85
	v_fmac_f32_e32 v17, s43, v85
	v_fmac_f32_e32 v18, s44, v85
	v_fmac_f32_e32 v19, s45, v85
	v_fmac_f32_e32 v20, s46, v85
	v_fmac_f32_e32 v21, s47, v85
	v_fmac_f32_e32 v22, s48, v85
	s_waitcnt vmcnt(19)
	v_readlane_b32 s32, v24, 44
	v_readlane_b32 s33, v25, 44
	v_readlane_b32 s34, v26, 44
	v_readlane_b32 s35, v27, 44
	v_readlane_b32 s36, v28, 44
	v_readlane_b32 s37, v29, 44
	v_readlane_b32 s38, v30, 44
	v_readlane_b32 s39, v31, 44
	v_readlane_b32 s40, v32, 44
	v_readlane_b32 s41, v33, 44
	v_readlane_b32 s42, v34, 44
	v_readlane_b32 s43, v35, 44
	v_readlane_b32 s44, v36, 44
	v_readlane_b32 s45, v37, 44
	v_readlane_b32 s46, v38, 44
	v_readlane_b32 s47, v39, 44
	v_readlane_b32 s48, v40, 44
	v_fmac_f32_e32 v6, s32, v86
	v_fmac_f32_e32 v7, s33, v86
	v_fmac_f32_e32 v8, s34, v86
	v_fmac_f32_e32 v9, s35, v86
	v_fmac_f32_e32 v10, s36, v86
	v_fmac_f32_e32 v11, s37, v86
	v_fmac_f32_e32 v12, s38, v86
	v_fmac_f32_e32 v13, s39, v86
	v_fmac_f32_e32 v14, s40, v86
	v_fmac_f32_e32 v15, s41, v86
	v_fmac_f32_e32 v16, s42, v86
	v_fmac_f32_e32 v17, s43, v86
	v_fmac_f32_e32 v18, s44, v86
	v_fmac_f32_e32 v19, s45, v86
	v_fmac_f32_e32 v20, s46, v86
	v_fmac_f32_e32 v21, s47, v86
	v_fmac_f32_e32 v22, s48, v86
	s_waitcnt vmcnt(18)
	v_readlane_b32 s32, v24, 45
	v_readlane_b32 s33, v25, 45
	v_readlane_b32 s34, v26, 45
	v_readlane_b32 s35, v27, 45
	v_readlane_b32 s36, v28, 45
	v_readlane_b32 s37, v29, 45
	v_readlane_b32 s38, v30, 45
	v_readlane_b32 s39, v31, 45
	v_readlane_b32 s40, v32, 45
	v_readlane_b32 s41, v33, 45
	v_readlane_b32 s42, v34, 45
	v_readlane_b32 s43, v35, 45
	v_readlane_b32 s44, v36, 45
	v_readlane_b32 s45, v37, 45
	v_readlane_b32 s46, v38, 45
	v_readlane_b32 s47, v39, 45
	v_readlane_b32 s48, v40, 45
	v_fmac_f32_e32 v6, s32, v87
	v_fmac_f32_e32 v7, s33, v87
	v_fmac_f32_e32 v8, s34, v87
	v_fmac_f32_e32 v9, s35, v87
	v_fmac_f32_e32 v10, s36, v87
	v_fmac_f32_e32 v11, s37, v87
	v_fmac_f32_e32 v12, s38, v87
	v_fmac_f32_e32 v13, s39, v87
	v_fmac_f32_e32 v14, s40, v87
	v_fmac_f32_e32 v15, s41, v87
	v_fmac_f32_e32 v16, s42, v87
	v_fmac_f32_e32 v17, s43, v87
	v_fmac_f32_e32 v18, s44, v87
	v_fmac_f32_e32 v19, s45, v87
	v_fmac_f32_e32 v20, s46, v87
	v_fmac_f32_e32 v21, s47, v87
	v_fmac_f32_e32 v22, s48, v87
	s_waitcnt vmcnt(17)
; DI void mods_item(const Params& p, int item, char* smem) {
;     ...
; #pragma unroll 8
;     for (int kk = 0; kk < 64; ++kk) {
;       float wv = W[(size_t)(k0 + kk) * 6144];
; #pragma unroll
;       for (int b = 0; b < 17; ++b) acc[b] += __shfl(s[b], kk, 64) * wv;
;     }
	v_readlane_b32 s32, v24, 46
	v_readlane_b32 s33, v25, 46
	v_readlane_b32 s34, v26, 46
	v_readlane_b32 s35, v27, 46
	v_readlane_b32 s36, v28, 46
	v_readlane_b32 s37, v29, 46
	v_readlane_b32 s38, v30, 46
	v_readlane_b32 s39, v31, 46
	v_readlane_b32 s40, v32, 46
	v_readlane_b32 s41, v33, 46
	v_readlane_b32 s42, v34, 46
	v_readlane_b32 s43, v35, 46
	v_readlane_b32 s44, v36, 46
	v_readlane_b32 s45, v37, 46
	v_readlane_b32 s46, v38, 46
	v_readlane_b32 s47, v39, 46
	v_readlane_b32 s48, v40, 46
	v_fmac_f32_e32 v6, s32, v88
	v_fmac_f32_e32 v7, s33, v88
	v_fmac_f32_e32 v8, s34, v88
	v_fmac_f32_e32 v9, s35, v88
	v_fmac_f32_e32 v10, s36, v88
	v_fmac_f32_e32 v11, s37, v88
	v_fmac_f32_e32 v12, s38, v88
	v_fmac_f32_e32 v13, s39, v88
	v_fmac_f32_e32 v14, s40, v88
	v_fmac_f32_e32 v15, s41, v88
	v_fmac_f32_e32 v16, s42, v88
	v_fmac_f32_e32 v17, s43, v88
	v_fmac_f32_e32 v18, s44, v88
	v_fmac_f32_e32 v19, s45, v88
	v_fmac_f32_e32 v20, s46, v88
	v_fmac_f32_e32 v21, s47, v88
	v_fmac_f32_e32 v22, s48, v88
	s_waitcnt vmcnt(16)
	v_readlane_b32 s32, v24, 47
	v_readlane_b32 s33, v25, 47
	v_readlane_b32 s34, v26, 47
	v_readlane_b32 s35, v27, 47
	v_readlane_b32 s36, v28, 47
	v_readlane_b32 s37, v29, 47
	v_readlane_b32 s38, v30, 47
	v_readlane_b32 s39, v31, 47
	v_readlane_b32 s40, v32, 47
	v_readlane_b32 s41, v33, 47
	v_readlane_b32 s42, v34, 47
	v_readlane_b32 s43, v35, 47
	v_readlane_b32 s44, v36, 47
	v_readlane_b32 s45, v37, 47
	v_readlane_b32 s46, v38, 47
	v_readlane_b32 s47, v39, 47
	v_readlane_b32 s48, v40, 47
	v_fmac_f32_e32 v6, s32, v89
	v_fmac_f32_e32 v7, s33, v89
	v_fmac_f32_e32 v8, s34, v89
	v_fmac_f32_e32 v9, s35, v89
	v_fmac_f32_e32 v10, s36, v89
	v_fmac_f32_e32 v11, s37, v89
	v_fmac_f32_e32 v12, s38, v89
	v_fmac_f32_e32 v13, s39, v89
	v_fmac_f32_e32 v14, s40, v89
	v_fmac_f32_e32 v15, s41, v89
	v_fmac_f32_e32 v16, s42, v89
	v_fmac_f32_e32 v17, s43, v89
	v_fmac_f32_e32 v18, s44, v89
	v_fmac_f32_e32 v19, s45, v89
	v_fmac_f32_e32 v20, s46, v89
	v_fmac_f32_e32 v21, s47, v89
	v_fmac_f32_e32 v22, s48, v89
	s_waitcnt vmcnt(15)
	v_readlane_b32 s32, v24, 48
	v_readlane_b32 s33, v25, 48
	v_readlane_b32 s34, v26, 48
	v_readlane_b32 s35, v27, 48
	v_readlane_b32 s36, v28, 48
	v_readlane_b32 s37, v29, 48
	v_readlane_b32 s38, v30, 48
	v_readlane_b32 s39, v31, 48
	v_readlane_b32 s40, v32, 48
	v_readlane_b32 s41, v33, 48
	v_readlane_b32 s42, v34, 48
	v_readlane_b32 s43, v35, 48
	v_readlane_b32 s44, v36, 48
	v_readlane_b32 s45, v37, 48
	v_readlane_b32 s46, v38, 48
	v_readlane_b32 s47, v39, 48
	v_readlane_b32 s48, v40, 48
	v_fmac_f32_e32 v6, s32, v90
	v_fmac_f32_e32 v7, s33, v90
	v_fmac_f32_e32 v8, s34, v90
	v_fmac_f32_e32 v9, s35, v90
	v_fmac_f32_e32 v10, s36, v90
	v_fmac_f32_e32 v11, s37, v90
	v_fmac_f32_e32 v12, s38, v90
	v_fmac_f32_e32 v13, s39, v90
	v_fmac_f32_e32 v14, s40, v90
	v_fmac_f32_e32 v15, s41, v90
	v_fmac_f32_e32 v16, s42, v90
	v_fmac_f32_e32 v17, s43, v90
	v_fmac_f32_e32 v18, s44, v90
	v_fmac_f32_e32 v19, s45, v90
	v_fmac_f32_e32 v20, s46, v90
	v_fmac_f32_e32 v21, s47, v90
	v_fmac_f32_e32 v22, s48, v90
	s_waitcnt vmcnt(14)
	v_readlane_b32 s32, v24, 49
	v_readlane_b32 s33, v25, 49
	v_readlane_b32 s34, v26, 49
	v_readlane_b32 s35, v27, 49
	v_readlane_b32 s36, v28, 49
	v_readlane_b32 s37, v29, 49
	v_readlane_b32 s38, v30, 49
	v_readlane_b32 s39, v31, 49
	v_readlane_b32 s40, v32, 49
	v_readlane_b32 s41, v33, 49
	v_readlane_b32 s42, v34, 49
	v_readlane_b32 s43, v35, 49
	v_readlane_b32 s44, v36, 49
	v_readlane_b32 s45, v37, 49
	v_readlane_b32 s46, v38, 49
	v_readlane_b32 s47, v39, 49
	v_readlane_b32 s48, v40, 49
	v_fmac_f32_e32 v6, s32, v91
	v_fmac_f32_e32 v7, s33, v91
	v_fmac_f32_e32 v8, s34, v91
	v_fmac_f32_e32 v9, s35, v91
	v_fmac_f32_e32 v10, s36, v91
	v_fmac_f32_e32 v11, s37, v91
	v_fmac_f32_e32 v12, s38, v91
	v_fmac_f32_e32 v13, s39, v91
	v_fmac_f32_e32 v14, s40, v91
	v_fmac_f32_e32 v15, s41, v91
	v_fmac_f32_e32 v16, s42, v91
	v_fmac_f32_e32 v17, s43, v91
	v_fmac_f32_e32 v18, s44, v91
	v_fmac_f32_e32 v19, s45, v91
	v_fmac_f32_e32 v20, s46, v91
	v_fmac_f32_e32 v21, s47, v91
	v_fmac_f32_e32 v22, s48, v91
	s_waitcnt vmcnt(13)
	v_readlane_b32 s32, v24, 50
	v_readlane_b32 s33, v25, 50
	v_readlane_b32 s34, v26, 50
	v_readlane_b32 s35, v27, 50
	v_readlane_b32 s36, v28, 50
	v_readlane_b32 s37, v29, 50
	v_readlane_b32 s38, v30, 50
	v_readlane_b32 s39, v31, 50
	v_readlane_b32 s40, v32, 50
	v_readlane_b32 s41, v33, 50
	v_readlane_b32 s42, v34, 50
	v_readlane_b32 s43, v35, 50
	v_readlane_b32 s44, v36, 50
	v_readlane_b32 s45, v37, 50
	v_readlane_b32 s46, v38, 50
	v_readlane_b32 s47, v39, 50
	v_readlane_b32 s48, v40, 50
	v_fmac_f32_e32 v6, s32, v92
	v_fmac_f32_e32 v7, s33, v92
	v_fmac_f32_e32 v8, s34, v92
	v_fmac_f32_e32 v9, s35, v92
	v_fmac_f32_e32 v10, s36, v92
	v_fmac_f32_e32 v11, s37, v92
	v_fmac_f32_e32 v12, s38, v92
	v_fmac_f32_e32 v13, s39, v92
	v_fmac_f32_e32 v14, s40, v92
	v_fmac_f32_e32 v15, s41, v92
	v_fmac_f32_e32 v16, s42, v92
	v_fmac_f32_e32 v17, s43, v92
	v_fmac_f32_e32 v18, s44, v92
	v_fmac_f32_e32 v19, s45, v92
	v_fmac_f32_e32 v20, s46, v92
	v_fmac_f32_e32 v21, s47, v92
	v_fmac_f32_e32 v22, s48, v92
	s_waitcnt vmcnt(12)
	v_readlane_b32 s32, v24, 51
	v_readlane_b32 s33, v25, 51
	v_readlane_b32 s34, v26, 51
	v_readlane_b32 s35, v27, 51
	v_readlane_b32 s36, v28, 51
	v_readlane_b32 s37, v29, 51
	v_readlane_b32 s38, v30, 51
	v_readlane_b32 s39, v31, 51
	v_readlane_b32 s40, v32, 51
	v_readlane_b32 s41, v33, 51
	v_readlane_b32 s42, v34, 51
	v_readlane_b32 s43, v35, 51
	v_readlane_b32 s44, v36, 51
	v_readlane_b32 s45, v37, 51
	v_readlane_b32 s46, v38, 51
	v_readlane_b32 s47, v39, 51
	v_readlane_b32 s48, v40, 51
	v_fmac_f32_e32 v6, s32, v93
	v_fmac_f32_e32 v7, s33, v93
	v_fmac_f32_e32 v8, s34, v93
	v_fmac_f32_e32 v9, s35, v93
	v_fmac_f32_e32 v10, s36, v93
	v_fmac_f32_e32 v11, s37, v93
	v_fmac_f32_e32 v12, s38, v93
	v_fmac_f32_e32 v13, s39, v93
	v_fmac_f32_e32 v14, s40, v93
	v_fmac_f32_e32 v15, s41, v93
	v_fmac_f32_e32 v16, s42, v93
	v_fmac_f32_e32 v17, s43, v93
	v_fmac_f32_e32 v18, s44, v93
	v_fmac_f32_e32 v19, s45, v93
	v_fmac_f32_e32 v20, s46, v93
	v_fmac_f32_e32 v21, s47, v93
	v_fmac_f32_e32 v22, s48, v93
	s_waitcnt vmcnt(11)
; DI void mods_item(const Params& p, int item, char* smem) {
;     ...
; #pragma unroll 8
;     for (int kk = 0; kk < 64; ++kk) {
;       float wv = W[(size_t)(k0 + kk) * 6144];
; #pragma unroll
;       for (int b = 0; b < 17; ++b) acc[b] += __shfl(s[b], kk, 64) * wv;
;     }
	v_readlane_b32 s32, v24, 52
	v_readlane_b32 s33, v25, 52
	v_readlane_b32 s34, v26, 52
	v_readlane_b32 s35, v27, 52
	v_readlane_b32 s36, v28, 52
	v_readlane_b32 s37, v29, 52
	v_readlane_b32 s38, v30, 52
	v_readlane_b32 s39, v31, 52
	v_readlane_b32 s40, v32, 52
	v_readlane_b32 s41, v33, 52
	v_readlane_b32 s42, v34, 52
	v_readlane_b32 s43, v35, 52
	v_readlane_b32 s44, v36, 52
	v_readlane_b32 s45, v37, 52
	v_readlane_b32 s46, v38, 52
	v_readlane_b32 s47, v39, 52
	v_readlane_b32 s48, v40, 52
	v_fmac_f32_e32 v6, s32, v94
	v_fmac_f32_e32 v7, s33, v94
	v_fmac_f32_e32 v8, s34, v94
	v_fmac_f32_e32 v9, s35, v94
	v_fmac_f32_e32 v10, s36, v94
	v_fmac_f32_e32 v11, s37, v94
	v_fmac_f32_e32 v12, s38, v94
	v_fmac_f32_e32 v13, s39, v94
	v_fmac_f32_e32 v14, s40, v94
	v_fmac_f32_e32 v15, s41, v94
	v_fmac_f32_e32 v16, s42, v94
	v_fmac_f32_e32 v17, s43, v94
	v_fmac_f32_e32 v18, s44, v94
	v_fmac_f32_e32 v19, s45, v94
	v_fmac_f32_e32 v20, s46, v94
	v_fmac_f32_e32 v21, s47, v94
	v_fmac_f32_e32 v22, s48, v94
	s_waitcnt vmcnt(10)
	v_readlane_b32 s32, v24, 53
	v_readlane_b32 s33, v25, 53
	v_readlane_b32 s34, v26, 53
	v_readlane_b32 s35, v27, 53
	v_readlane_b32 s36, v28, 53
	v_readlane_b32 s37, v29, 53
	v_readlane_b32 s38, v30, 53
	v_readlane_b32 s39, v31, 53
	v_readlane_b32 s40, v32, 53
	v_readlane_b32 s41, v33, 53
	v_readlane_b32 s42, v34, 53
	v_readlane_b32 s43, v35, 53
	v_readlane_b32 s44, v36, 53
	v_readlane_b32 s45, v37, 53
	v_readlane_b32 s46, v38, 53
	v_readlane_b32 s47, v39, 53
	v_readlane_b32 s48, v40, 53
	v_fmac_f32_e32 v6, s32, v95
	v_fmac_f32_e32 v7, s33, v95
	v_fmac_f32_e32 v8, s34, v95
	v_fmac_f32_e32 v9, s35, v95
	v_fmac_f32_e32 v10, s36, v95
	v_fmac_f32_e32 v11, s37, v95
	v_fmac_f32_e32 v12, s38, v95
	v_fmac_f32_e32 v13, s39, v95
	v_fmac_f32_e32 v14, s40, v95
	v_fmac_f32_e32 v15, s41, v95
	v_fmac_f32_e32 v16, s42, v95
	v_fmac_f32_e32 v17, s43, v95
	v_fmac_f32_e32 v18, s44, v95
	v_fmac_f32_e32 v19, s45, v95
	v_fmac_f32_e32 v20, s46, v95
	v_fmac_f32_e32 v21, s47, v95
	v_fmac_f32_e32 v22, s48, v95
	s_waitcnt vmcnt(9)
	v_readlane_b32 s32, v24, 54
	v_readlane_b32 s33, v25, 54
	v_readlane_b32 s34, v26, 54
	v_readlane_b32 s35, v27, 54
	v_readlane_b32 s36, v28, 54
	v_readlane_b32 s37, v29, 54
	v_readlane_b32 s38, v30, 54
	v_readlane_b32 s39, v31, 54
	v_readlane_b32 s40, v32, 54
	v_readlane_b32 s41, v33, 54
	v_readlane_b32 s42, v34, 54
	v_readlane_b32 s43, v35, 54
	v_readlane_b32 s44, v36, 54
	v_readlane_b32 s45, v37, 54
	v_readlane_b32 s46, v38, 54
	v_readlane_b32 s47, v39, 54
	v_readlane_b32 s48, v40, 54
	v_fmac_f32_e32 v6, s32, v96
	v_fmac_f32_e32 v7, s33, v96
	v_fmac_f32_e32 v8, s34, v96
	v_fmac_f32_e32 v9, s35, v96
	v_fmac_f32_e32 v10, s36, v96
	v_fmac_f32_e32 v11, s37, v96
	v_fmac_f32_e32 v12, s38, v96
	v_fmac_f32_e32 v13, s39, v96
	v_fmac_f32_e32 v14, s40, v96
	v_fmac_f32_e32 v15, s41, v96
	v_fmac_f32_e32 v16, s42, v96
	v_fmac_f32_e32 v17, s43, v96
	v_fmac_f32_e32 v18, s44, v96
	v_fmac_f32_e32 v19, s45, v96
	v_fmac_f32_e32 v20, s46, v96
	v_fmac_f32_e32 v21, s47, v96
	v_fmac_f32_e32 v22, s48, v96
	s_waitcnt vmcnt(8)
	v_readlane_b32 s32, v24, 55
	v_readlane_b32 s33, v25, 55
	v_readlane_b32 s34, v26, 55
	v_readlane_b32 s35, v27, 55
	v_readlane_b32 s36, v28, 55
	v_readlane_b32 s37, v29, 55
	v_readlane_b32 s38, v30, 55
	v_readlane_b32 s39, v31, 55
	v_readlane_b32 s40, v32, 55
	v_readlane_b32 s41, v33, 55
	v_readlane_b32 s42, v34, 55
	v_readlane_b32 s43, v35, 55
	v_readlane_b32 s44, v36, 55
	v_readlane_b32 s45, v37, 55
	v_readlane_b32 s46, v38, 55
	v_readlane_b32 s47, v39, 55
	v_readlane_b32 s48, v40, 55
	v_fmac_f32_e32 v6, s32, v97
	v_fmac_f32_e32 v7, s33, v97
	v_fmac_f32_e32 v8, s34, v97
	v_fmac_f32_e32 v9, s35, v97
	v_fmac_f32_e32 v10, s36, v97
	v_fmac_f32_e32 v11, s37, v97
	v_fmac_f32_e32 v12, s38, v97
	v_fmac_f32_e32 v13, s39, v97
	v_fmac_f32_e32 v14, s40, v97
	v_fmac_f32_e32 v15, s41, v97
	v_fmac_f32_e32 v16, s42, v97
	v_fmac_f32_e32 v17, s43, v97
	v_fmac_f32_e32 v18, s44, v97
	v_fmac_f32_e32 v19, s45, v97
	v_fmac_f32_e32 v20, s46, v97
	v_fmac_f32_e32 v21, s47, v97
	v_fmac_f32_e32 v22, s48, v97
	s_waitcnt vmcnt(7)
	v_readlane_b32 s32, v24, 56
	v_readlane_b32 s33, v25, 56
	v_readlane_b32 s34, v26, 56
	v_readlane_b32 s35, v27, 56
	v_readlane_b32 s36, v28, 56
	v_readlane_b32 s37, v29, 56
	v_readlane_b32 s38, v30, 56
	v_readlane_b32 s39, v31, 56
	v_readlane_b32 s40, v32, 56
	v_readlane_b32 s41, v33, 56
	v_readlane_b32 s42, v34, 56
	v_readlane_b32 s43, v35, 56
	v_readlane_b32 s44, v36, 56
	v_readlane_b32 s45, v37, 56
	v_readlane_b32 s46, v38, 56
	v_readlane_b32 s47, v39, 56
	v_readlane_b32 s48, v40, 56
	v_fmac_f32_e32 v6, s32, v98
	v_fmac_f32_e32 v7, s33, v98
	v_fmac_f32_e32 v8, s34, v98
	v_fmac_f32_e32 v9, s35, v98
	v_fmac_f32_e32 v10, s36, v98
	v_fmac_f32_e32 v11, s37, v98
	v_fmac_f32_e32 v12, s38, v98
	v_fmac_f32_e32 v13, s39, v98
	v_fmac_f32_e32 v14, s40, v98
	v_fmac_f32_e32 v15, s41, v98
	v_fmac_f32_e32 v16, s42, v98
	v_fmac_f32_e32 v17, s43, v98
	v_fmac_f32_e32 v18, s44, v98
	v_fmac_f32_e32 v19, s45, v98
	v_fmac_f32_e32 v20, s46, v98
	v_fmac_f32_e32 v21, s47, v98
	v_fmac_f32_e32 v22, s48, v98
	s_waitcnt vmcnt(6)
	v_readlane_b32 s32, v24, 57
	v_readlane_b32 s33, v25, 57
	v_readlane_b32 s34, v26, 57
	v_readlane_b32 s35, v27, 57
	v_readlane_b32 s36, v28, 57
	v_readlane_b32 s37, v29, 57
	v_readlane_b32 s38, v30, 57
	v_readlane_b32 s39, v31, 57
	v_readlane_b32 s40, v32, 57
	v_readlane_b32 s41, v33, 57
	v_readlane_b32 s42, v34, 57
	v_readlane_b32 s43, v35, 57
	v_readlane_b32 s44, v36, 57
	v_readlane_b32 s45, v37, 57
	v_readlane_b32 s46, v38, 57
	v_readlane_b32 s47, v39, 57
	v_readlane_b32 s48, v40, 57
	v_fmac_f32_e32 v6, s32, v99
	v_fmac_f32_e32 v7, s33, v99
	v_fmac_f32_e32 v8, s34, v99
	v_fmac_f32_e32 v9, s35, v99
	v_fmac_f32_e32 v10, s36, v99
	v_fmac_f32_e32 v11, s37, v99
	v_fmac_f32_e32 v12, s38, v99
	v_fmac_f32_e32 v13, s39, v99
	v_fmac_f32_e32 v14, s40, v99
	v_fmac_f32_e32 v15, s41, v99
	v_fmac_f32_e32 v16, s42, v99
	v_fmac_f32_e32 v17, s43, v99
	v_fmac_f32_e32 v18, s44, v99
	v_fmac_f32_e32 v19, s45, v99
	v_fmac_f32_e32 v20, s46, v99
	v_fmac_f32_e32 v21, s47, v99
	v_fmac_f32_e32 v22, s48, v99
	s_waitcnt vmcnt(5)
; DI float siluf_(float x) { return x * frcp(1.f + __expf(-x)); }
; DI void mods_item(const Params& p, int item, char* smem) {
;     ...
;   for (int kb = 0; kb < 4; ++kb) {
;     const int k0 = wid * 256 + kb * 64;
;     float s[17];
; #pragma unroll
;     for (int b = 0; b < 17; ++b) {
;       float cv = (b < 16) ? p.c[b * 1024 + k0 + lane] : p.c_ctx[k0 + lane];
;       s[b] = siluf_(cv);
;     }
; #pragma unroll 8
;     for (int kk = 0; kk < 64; ++kk) {
;       float wv = W[(size_t)(k0 + kk) * 6144];
; #pragma unroll
;       for (int b = 0; b < 17; ++b) acc[b] += __shfl(s[b], kk, 64) * wv;
;     }
	v_readlane_b32 s32, v24, 58
	v_readlane_b32 s33, v25, 58
	v_readlane_b32 s34, v26, 58
	v_readlane_b32 s35, v27, 58
	v_readlane_b32 s36, v28, 58
	v_readlane_b32 s37, v29, 58
	v_readlane_b32 s38, v30, 58
	v_readlane_b32 s39, v31, 58
	v_readlane_b32 s40, v32, 58
	v_readlane_b32 s41, v33, 58
	v_readlane_b32 s42, v34, 58
	v_readlane_b32 s43, v35, 58
	v_readlane_b32 s44, v36, 58
	v_readlane_b32 s45, v37, 58
	v_readlane_b32 s46, v38, 58
	v_readlane_b32 s47, v39, 58
	v_readlane_b32 s48, v40, 58
	v_fmac_f32_e32 v6, s32, v100
	v_fmac_f32_e32 v7, s33, v100
	v_fmac_f32_e32 v8, s34, v100
	v_fmac_f32_e32 v9, s35, v100
	v_fmac_f32_e32 v10, s36, v100
	v_fmac_f32_e32 v11, s37, v100
	v_fmac_f32_e32 v12, s38, v100
	v_fmac_f32_e32 v13, s39, v100
	v_fmac_f32_e32 v14, s40, v100
	v_fmac_f32_e32 v15, s41, v100
	v_fmac_f32_e32 v16, s42, v100
	v_fmac_f32_e32 v17, s43, v100
	v_fmac_f32_e32 v18, s44, v100
	v_fmac_f32_e32 v19, s45, v100
	v_fmac_f32_e32 v20, s46, v100
	v_fmac_f32_e32 v21, s47, v100
	v_fmac_f32_e32 v22, s48, v100
	s_waitcnt vmcnt(4)
	v_readlane_b32 s32, v24, 59
	v_readlane_b32 s33, v25, 59
	v_readlane_b32 s34, v26, 59
	v_readlane_b32 s35, v27, 59
	v_readlane_b32 s36, v28, 59
	v_readlane_b32 s37, v29, 59
	v_readlane_b32 s38, v30, 59
	v_readlane_b32 s39, v31, 59
	v_readlane_b32 s40, v32, 59
	v_readlane_b32 s41, v33, 59
	v_readlane_b32 s42, v34, 59
	v_readlane_b32 s43, v35, 59
	v_readlane_b32 s44, v36, 59
	v_readlane_b32 s45, v37, 59
	v_readlane_b32 s46, v38, 59
	v_readlane_b32 s47, v39, 59
	v_readlane_b32 s48, v40, 59
	v_fmac_f32_e32 v6, s32, v101
	v_fmac_f32_e32 v7, s33, v101
	v_fmac_f32_e32 v8, s34, v101
	v_fmac_f32_e32 v9, s35, v101
	v_fmac_f32_e32 v10, s36, v101
	v_fmac_f32_e32 v11, s37, v101
	v_fmac_f32_e32 v12, s38, v101
	v_fmac_f32_e32 v13, s39, v101
	v_fmac_f32_e32 v14, s40, v101
	v_fmac_f32_e32 v15, s41, v101
	v_fmac_f32_e32 v16, s42, v101
	v_fmac_f32_e32 v17, s43, v101
	v_fmac_f32_e32 v18, s44, v101
	v_fmac_f32_e32 v19, s45, v101
	v_fmac_f32_e32 v20, s46, v101
	v_fmac_f32_e32 v21, s47, v101
	v_fmac_f32_e32 v22, s48, v101
	s_waitcnt vmcnt(3)
	v_readlane_b32 s32, v24, 60
	v_readlane_b32 s33, v25, 60
	v_readlane_b32 s34, v26, 60
	v_readlane_b32 s35, v27, 60
	v_readlane_b32 s36, v28, 60
	v_readlane_b32 s37, v29, 60
	v_readlane_b32 s38, v30, 60
	v_readlane_b32 s39, v31, 60
	v_readlane_b32 s40, v32, 60
	v_readlane_b32 s41, v33, 60
	v_readlane_b32 s42, v34, 60
	v_readlane_b32 s43, v35, 60
	v_readlane_b32 s44, v36, 60
	v_readlane_b32 s45, v37, 60
	v_readlane_b32 s46, v38, 60
	v_readlane_b32 s47, v39, 60
	v_readlane_b32 s48, v40, 60
	v_fmac_f32_e32 v6, s32, v102
	v_fmac_f32_e32 v7, s33, v102
	v_fmac_f32_e32 v8, s34, v102
	v_fmac_f32_e32 v9, s35, v102
	v_fmac_f32_e32 v10, s36, v102
	v_fmac_f32_e32 v11, s37, v102
	v_fmac_f32_e32 v12, s38, v102
	v_fmac_f32_e32 v13, s39, v102
	v_fmac_f32_e32 v14, s40, v102
	v_fmac_f32_e32 v15, s41, v102
	v_fmac_f32_e32 v16, s42, v102
	v_fmac_f32_e32 v17, s43, v102
	v_fmac_f32_e32 v18, s44, v102
	v_fmac_f32_e32 v19, s45, v102
	v_fmac_f32_e32 v20, s46, v102
	v_fmac_f32_e32 v21, s47, v102
	v_fmac_f32_e32 v22, s48, v102
	s_waitcnt vmcnt(2)
	v_readlane_b32 s32, v24, 61
	v_readlane_b32 s33, v25, 61
	v_readlane_b32 s34, v26, 61
	v_readlane_b32 s35, v27, 61
	v_readlane_b32 s36, v28, 61
	v_readlane_b32 s37, v29, 61
	v_readlane_b32 s38, v30, 61
	v_readlane_b32 s39, v31, 61
	v_readlane_b32 s40, v32, 61
	v_readlane_b32 s41, v33, 61
	v_readlane_b32 s42, v34, 61
	v_readlane_b32 s43, v35, 61
	v_readlane_b32 s44, v36, 61
	v_readlane_b32 s45, v37, 61
	v_readlane_b32 s46, v38, 61
	v_readlane_b32 s47, v39, 61
	v_readlane_b32 s48, v40, 61
	v_fmac_f32_e32 v6, s32, v103
	v_fmac_f32_e32 v7, s33, v103
	v_fmac_f32_e32 v8, s34, v103
	v_fmac_f32_e32 v9, s35, v103
	v_fmac_f32_e32 v10, s36, v103
	v_fmac_f32_e32 v11, s37, v103
	v_fmac_f32_e32 v12, s38, v103
	v_fmac_f32_e32 v13, s39, v103
	v_fmac_f32_e32 v14, s40, v103
	v_fmac_f32_e32 v15, s41, v103
	v_fmac_f32_e32 v16, s42, v103
	v_fmac_f32_e32 v17, s43, v103
	v_fmac_f32_e32 v18, s44, v103
	v_fmac_f32_e32 v19, s45, v103
	v_fmac_f32_e32 v20, s46, v103
	v_fmac_f32_e32 v21, s47, v103
	v_fmac_f32_e32 v22, s48, v103
	s_waitcnt vmcnt(1)
	v_readlane_b32 s32, v24, 62
	v_readlane_b32 s33, v25, 62
	v_readlane_b32 s34, v26, 62
	v_readlane_b32 s35, v27, 62
	v_readlane_b32 s36, v28, 62
	v_readlane_b32 s37, v29, 62
	v_readlane_b32 s38, v30, 62
	v_readlane_b32 s39, v31, 62
	v_readlane_b32 s40, v32, 62
	v_readlane_b32 s41, v33, 62
	v_readlane_b32 s42, v34, 62
	v_readlane_b32 s43, v35, 62
	v_readlane_b32 s44, v36, 62
	v_readlane_b32 s45, v37, 62
	v_readlane_b32 s46, v38, 62
	v_readlane_b32 s47, v39, 62
	v_readlane_b32 s48, v40, 62
	v_fmac_f32_e32 v6, s32, v104
	v_fmac_f32_e32 v7, s33, v104
	v_fmac_f32_e32 v8, s34, v104
	v_fmac_f32_e32 v9, s35, v104
	v_fmac_f32_e32 v10, s36, v104
	v_fmac_f32_e32 v11, s37, v104
	v_fmac_f32_e32 v12, s38, v104
	v_fmac_f32_e32 v13, s39, v104
	v_fmac_f32_e32 v14, s40, v104
	v_fmac_f32_e32 v15, s41, v104
	v_fmac_f32_e32 v16, s42, v104
	v_fmac_f32_e32 v17, s43, v104
	v_fmac_f32_e32 v18, s44, v104
	v_fmac_f32_e32 v19, s45, v104
	v_fmac_f32_e32 v20, s46, v104
	v_fmac_f32_e32 v21, s47, v104
	v_fmac_f32_e32 v22, s48, v104
	s_waitcnt vmcnt(0)
	v_readlane_b32 s32, v24, 63
	v_readlane_b32 s33, v25, 63
	v_readlane_b32 s34, v26, 63
	v_readlane_b32 s35, v27, 63
	v_readlane_b32 s36, v28, 63
	v_readlane_b32 s37, v29, 63
	v_readlane_b32 s38, v30, 63
	v_readlane_b32 s39, v31, 63
	v_readlane_b32 s40, v32, 63
	v_readlane_b32 s41, v33, 63
	v_readlane_b32 s42, v34, 63
	v_readlane_b32 s43, v35, 63
	v_readlane_b32 s44, v36, 63
	v_readlane_b32 s45, v37, 63
	v_readlane_b32 s46, v38, 63
	v_readlane_b32 s47, v39, 63
	v_readlane_b32 s48, v40, 63
	v_fmac_f32_e32 v6, s32, v105
	v_fmac_f32_e32 v7, s33, v105
	v_fmac_f32_e32 v8, s34, v105
	v_fmac_f32_e32 v9, s35, v105
	v_fmac_f32_e32 v10, s36, v105
	v_fmac_f32_e32 v11, s37, v105
	v_fmac_f32_e32 v12, s38, v105
	v_fmac_f32_e32 v13, s39, v105
	v_fmac_f32_e32 v14, s40, v105
	v_fmac_f32_e32 v15, s41, v105
	v_fmac_f32_e32 v16, s42, v105
	v_fmac_f32_e32 v17, s43, v105
	v_fmac_f32_e32 v18, s44, v105
	v_fmac_f32_e32 v19, s45, v105
	v_fmac_f32_e32 v20, s46, v105
	v_fmac_f32_e32 v21, s47, v105
	v_fmac_f32_e32 v22, s48, v105
	s_add_u32 s24, s24, 256
	s_addc_u32 s25, s25, 0
	s_add_u32 s8, s8, 256
	s_addc_u32 s9, s9, 0
	s_add_i32 s20, s20, 1
	s_cmp_lt_u32 s20, 4
	s_cbranch_scc1 .Lmods_kb
; DI void mods_item(const Params& p, int item, char* smem) {
;     ...
;   float* red = (float*)smem;
;   __syncthreads();
; #pragma unroll
;   for (int b = 0; b < 17; ++b) red[(wid * 17 + b) * 64 + lane] = acc[b];
;   __syncthreads();
;   float* mo = (float*)(p.ws + OFF_MODS);
;   for (int e = tid; e < 17 * 64; e += 256) {
;     int b = e >> 6, cc = e & 63;
;     float v = red[(0 * 17 + b) * 64 + cc] + red[(1 * 17 + b) * 64 + cc] + red[(2 * 17 + b) * 64 + cc] +
;               red[(3 * 17 + b) * 64 + cc] + p.mod_b[l * 6144 + cg0 + cc];
;     mo[(size_t)(l * 17 + b) * 6144 + cg0 + cc] = v;
;   }
;   __syncthreads();
	s_barrier
	s_mul_i32 s26, s19, 4352
	v_add_u32_e32 v106, s26, v111
	ds_write_b32 v106, v6 offset:0
	ds_write_b32 v106, v7 offset:256
	ds_write_b32 v106, v8 offset:512
	ds_write_b32 v106, v9 offset:768
	ds_write_b32 v106, v10 offset:1024
	ds_write_b32 v106, v11 offset:1280
	ds_write_b32 v106, v12 offset:1536
	ds_write_b32 v106, v13 offset:1792
	ds_write_b32 v106, v14 offset:2048
	ds_write_b32 v106, v15 offset:2304
	ds_write_b32 v106, v16 offset:2560
	ds_write_b32 v106, v17 offset:2816
	ds_write_b32 v106, v18 offset:3072
	ds_write_b32 v106, v19 offset:3328
	ds_write_b32 v106, v20 offset:3584
	ds_write_b32 v106, v21 offset:3840
	ds_write_b32 v106, v22 offset:4096
	s_waitcnt lgkmcnt(0)
	s_barrier
	v_and_b32_e32 v107, 0xff, v196
	s_mul_i32 s26, s17, 6144
	s_add_u32 s26, s26, s18
	s_lshl_b32 s26, s26, 2
	s_add_u32 s28, s12, s26
	s_addc_u32 s29, s13, 0
	s_mul_i32 s26, s17, 104448
	s_add_u32 s26, s26, s18
	s_lshl_b32 s26, s26, 2
	s_add_u32 s30, s14, 0x1da60000
	s_addc_u32 s31, s15, 0
	s_add_u32 s30, s30, s26
	s_addc_u32 s31, s31, 0
	v_and_b32_e32 v108, 63, v107
	v_lshlrev_b32_e32 v108, 2, v108
	global_load_dword v110, v108, s[28:29]
	v_lshlrev_b32_e32 v106, 2, v107
	ds_read_b32 v42, v106 offset:0
	ds_read_b32 v43, v106 offset:4352
	ds_read_b32 v44, v106 offset:8704
	ds_read_b32 v45, v106 offset:13056
	v_lshrrev_b32_e32 v109, 6, v107
	v_add_u32_e32 v109, 0, v109
	v_mul_u32_u24_e32 v109, 24576, v109
	v_add_u32_e32 v109, v109, v108
	s_waitcnt vmcnt(0) lgkmcnt(0)
	v_add_f32_e32 v42, v42, v43
	v_add_f32_e32 v42, v42, v44
	v_add_f32_e32 v42, v42, v45
	v_add_f32_e32 v42, v42, v110
	global_store_dword v109, v42, s[30:31]
	v_lshlrev_b32_e32 v106, 2, v107
	ds_read_b32 v42, v106 offset:1024
	ds_read_b32 v43, v106 offset:5376
	ds_read_b32 v44, v106 offset:9728
	ds_read_b32 v45, v106 offset:14080
	v_lshrrev_b32_e32 v109, 6, v107
	v_add_u32_e32 v109, 4, v109
	v_mul_u32_u24_e32 v109, 24576, v109
	v_add_u32_e32 v109, v109, v108
	s_waitcnt vmcnt(0) lgkmcnt(0)
	v_add_f32_e32 v42, v42, v43
	v_add_f32_e32 v42, v42, v44
	v_add_f32_e32 v42, v42, v45
	v_add_f32_e32 v42, v42, v110
	global_store_dword v109, v42, s[30:31]
	v_lshlrev_b32_e32 v106, 2, v107
	ds_read_b32 v42, v106 offset:2048
	ds_read_b32 v43, v106 offset:6400
	ds_read_b32 v44, v106 offset:10752
	ds_read_b32 v45, v106 offset:15104
	v_lshrrev_b32_e32 v109, 6, v107
	v_add_u32_e32 v109, 8, v109
	v_mul_u32_u24_e32 v109, 24576, v109
	v_add_u32_e32 v109, v109, v108
	s_waitcnt vmcnt(0) lgkmcnt(0)
	v_add_f32_e32 v42, v42, v43
	v_add_f32_e32 v42, v42, v44
	v_add_f32_e32 v42, v42, v45
	v_add_f32_e32 v42, v42, v110
	global_store_dword v109, v42, s[30:31]
	v_lshlrev_b32_e32 v106, 2, v107
	ds_read_b32 v42, v106 offset:3072
	ds_read_b32 v43, v106 offset:7424
	ds_read_b32 v44, v106 offset:11776
	ds_read_b32 v45, v106 offset:16128
	v_lshrrev_b32_e32 v109, 6, v107
	v_add_u32_e32 v109, 12, v109
	v_mul_u32_u24_e32 v109, 24576, v109
	v_add_u32_e32 v109, v109, v108
	s_waitcnt vmcnt(0) lgkmcnt(0)
	v_add_f32_e32 v42, v42, v43
	v_add_f32_e32 v42, v42, v44
	v_add_f32_e32 v42, v42, v45
	v_add_f32_e32 v42, v42, v110
	global_store_dword v109, v42, s[30:31]
	s_cmp_eq_u32 s19, 0
	s_cbranch_scc0 .Lmods_done
	v_lshlrev_b32_e32 v106, 2, v107
	ds_read_b32 v42, v106 offset:4096
	ds_read_b32 v43, v106 offset:8448
	ds_read_b32 v44, v106 offset:12800
	ds_read_b32 v45, v106 offset:17152
	v_lshrrev_b32_e32 v109, 6, v107
	v_add_u32_e32 v109, 16, v109
	v_mul_u32_u24_e32 v109, 24576, v109
	v_add_u32_e32 v109, v109, v108
	s_waitcnt vmcnt(0) lgkmcnt(0)
	v_add_f32_e32 v42, v42, v43
	v_add_f32_e32 v42, v42, v44
	v_add_f32_e32 v42, v42, v45
	v_add_f32_e32 v42, v42, v110
	global_store_dword v109, v42, s[30:31]
.Lmods_done:
	s_waitcnt vmcnt(0) lgkmcnt(0)
	s_barrier
	v_readlane_b32 s0, v255, 0
	v_readlane_b32 s1, v255, 1
	v_readlane_b32 s2, v255, 2
	v_readlane_b32 s3, v255, 3
	v_readlane_b32 s4, v255, 4
	v_readlane_b32 s5, v255, 5
	v_readlane_b32 s6, v255, 6
	v_readlane_b32 s7, v255, 7
	v_readlane_b32 s8, v255, 8
	v_readlane_b32 s9, v255, 9
	v_readlane_b32 s10, v255, 10
	v_readlane_b32 s11, v255, 11
	v_readlane_b32 s12, v255, 12
	v_readlane_b32 s13, v255, 13
	v_readlane_b32 s14, v255, 14
	v_readlane_b32 s15, v255, 15
	v_readlane_b32 s16, v255, 16
	v_readlane_b32 s17, v255, 17
	v_readlane_b32 s18, v255, 18
	v_readlane_b32 s19, v255, 19
	v_readlane_b32 s20, v255, 20
	v_readlane_b32 s21, v255, 21
	v_readlane_b32 s22, v255, 22
	v_readlane_b32 s23, v255, 23
	v_readlane_b32 s24, v255, 24
	v_readlane_b32 s25, v255, 25
	v_readlane_b32 s26, v255, 26
	v_readlane_b32 s27, v255, 27
	v_readlane_b32 s28, v255, 28
	v_readlane_b32 s29, v255, 29
	v_readlane_b32 s30, v255, 30
	v_readlane_b32 s31, v255, 31
	v_readlane_b32 s32, v255, 32
	v_readlane_b32 s33, v255, 33
	v_readlane_b32 s34, v255, 34
	v_readlane_b32 s35, v255, 35
	v_readlane_b32 s36, v255, 36
	v_readlane_b32 s37, v255, 37
	v_readlane_b32 s38, v255, 38
	v_readlane_b32 s39, v255, 39
	v_readlane_b32 s40, v255, 40
	v_readlane_b32 s41, v255, 41
	v_readlane_b32 s42, v255, 42
	v_readlane_b32 s43, v255, 43
	v_readlane_b32 s44, v255, 44
	v_readlane_b32 s45, v255, 45
	v_readlane_b32 s46, v255, 46
	v_readlane_b32 s47, v255, 47
	v_readlane_b32 s48, v255, 48
	v_readlane_b32 s49, v255, 49
.LBB0_909:
	v_readlane_b32 s6, v243, 7
	s_mov_b64 s[4:5], -1
	s_mov_b64 s[0:1], 0
	s_cmp_lt_i32 s6, 23
	s_mov_b64 s[22:23], 0
	s_cbranch_scc0 .LBB0_914
	s_andn2_b64 vcc, exec, s[4:5]
	s_cbranch_vccz .LBB0_915
